# GEMM K-loops: s_setprio flips deleted (no VALU left in the load segments for priority to arbitrate)
# speedup vs baseline: 1.0159x; 1.0159x over previous
; #define PG8_STAGE(bufoff, gbase, voff) do { _Pragma("unroll") for (int _i = 0; _i < 2; ++_i) \
;         __builtin_amdgcn_global_load_lds((const unsigned*)((const char*)(gbase) + (voff)[_i]), (LAS unsigned*)(lds + (bufoff) + ldsw + _i * 8192), 16, 0, 0); } while (0)
; #define PG8_LDA(dst, b, h) do { _Pragma("unroll") for (int m = 0; m < 4; ++m) _Pragma("unroll") for (int k = 0; k < 2; ++k) dst[m][k] = *(const LAS bf16x8*)(lds + PG8_SA(b, h) + aoff + m * 2048 + k * 1024); } while (0)
; #define PG8_LDB(dst, b, h) do { _Pragma("unroll") for (int n = 0; n < 2; ++n) _Pragma("unroll") for (int k = 0; k < 2; ++k) dst[n][k] = *(const LAS bf16x8*)(lds + PG8_SB(b, h) + boff + n * 2048 + k * 1024); } while (0)
; #define PG8_MMA(ai, bj, At, Bt) do { __builtin_amdgcn_s_setprio(1); _Pragma("unroll") for (int m = 0; m < 4; ++m) _Pragma("unroll") for (int n = 0; n < 2; ++n) _Pragma("unroll") for (int k = 0; k < 2; ++k) \
;         acc[ai][bj][m][n] = __builtin_amdgcn_mfma_f32_16x16x32_bf16(Bt[n][k], At[m][k], acc[ai][bj][m][n], 0, 0, 0); __builtin_amdgcn_s_setprio(0); } while (0)
; #define PG8_WAIT_V(n) asm volatile("s_waitcnt vmcnt(" #n ")" ::: "memory")
; #define PG8_WAIT_L(n) asm volatile("s_waitcnt lgkmcnt(" #n ")" ::: "memory")
; #define PG8_BAR __builtin_amdgcn_s_barrier()
; #define PG8_SCHED __builtin_amdgcn_sched_barrier(0)
; template <class Epi>
; __device__ __forceinline__ void gemm_phase(LAS unsigned char* lds, const Gemm g, const StaticOrder& S, const Epi& E) {
;     ...
;             PG8_LDB(B0, 0, 0); PG8_SCHED; PG8_LDA(At, 0, 0); PG8_STAGE(PG8_SA(1, 1), a1 + hstep, voffA);
;             PG8_WAIT_L(8); PG8_BAR; PG8_WAIT_L(0); PG8_MMA(0, 0, At, B0); PG8_BAR; PG8_SCHED;
;             PG8_LDB(B1, 0, 1); PG8_STAGE(PG8_SB(0, 0), b2, voffB);
;             PG8_BAR; PG8_WAIT_L(0); PG8_MMA(0, 1, At, B1); PG8_BAR;
;             PG8_LDA(At, 0, 1); PG8_STAGE(PG8_SA(0, 0), a2, voffA);
;             PG8_BAR; PG8_WAIT_L(0); PG8_MMA(1, 0, At, B0); PG8_BAR; PG8_SCHED;
;             PG8_STAGE(PG8_SB(0, 1), b2 + hstep, voffB);
;             PG8_WAIT_V(6); PG8_BAR; PG8_MMA(1, 1, At, B1); PG8_BAR;
.LBB0_64:
	s_add_u32 s58, s56, 0xfff80080
	s_addc_u32 s59, s57, -1
	s_add_i32 s86, 0, 0x10000
	s_cmp_eq_u32 s85, 28
	s_cselect_b32 s61, s49, s59
	s_cselect_b32 s60, s81, s58
	s_cselect_b32 s59, s47, s84
	s_cselect_b32 s58, s82, s83
	s_add_i32 m0, s55, 0xc000
	ds_read_b128 v[170:173], v151
	ds_read_b128 v[174:177], v151 offset:1024
	ds_read_b128 v[178:181], v151 offset:2048
	ds_read_b128 v[182:185], v151 offset:3072
	ds_read_b128 v[186:189], v151 offset:4096
	ds_read_b128 v[190:193], v151 offset:5120
	ds_read_b128 v[194:197], v151 offset:6144
	ds_read_b128 v[198:201], v151 offset:7168
	global_load_lds_dwordx4 v136, s[56:57]
	s_add_i32 m0, s55, 0xe000
	s_nop 0
	global_load_lds_dwordx4 v138, s[56:57]
	s_waitcnt lgkmcnt(8)
	s_barrier
	s_waitcnt lgkmcnt(0)
	v_mfma_f32_16x16x32_bf16 v[126:129], v[154:157], v[170:173], v[126:129]
	v_mfma_f32_16x16x32_bf16 v[122:125], v[162:165], v[170:173], v[122:125]
	v_mfma_f32_16x16x32_bf16 v[110:113], v[154:157], v[178:181], v[110:113]
	v_mfma_f32_16x16x32_bf16 v[106:109], v[162:165], v[178:181], v[106:109]
	v_mfma_f32_16x16x32_bf16 v[94:97], v[154:157], v[186:189], v[94:97]
	v_mfma_f32_16x16x32_bf16 v[90:93], v[162:165], v[186:189], v[90:93]
	v_mfma_f32_16x16x32_bf16 v[78:81], v[154:157], v[194:197], v[78:81]
	v_mfma_f32_16x16x32_bf16 v[74:77], v[162:165], v[194:197], v[74:77]
	v_mfma_f32_16x16x32_bf16 v[126:129], v[158:161], v[174:177], v[126:129]
	v_mfma_f32_16x16x32_bf16 v[122:125], v[166:169], v[174:177], v[122:125]
	v_mfma_f32_16x16x32_bf16 v[110:113], v[158:161], v[182:185], v[110:113]
	v_mfma_f32_16x16x32_bf16 v[106:109], v[166:169], v[182:185], v[106:109]
	v_mfma_f32_16x16x32_bf16 v[94:97], v[158:161], v[190:193], v[94:97]
	v_mfma_f32_16x16x32_bf16 v[90:93], v[166:169], v[190:193], v[90:93]
	v_mfma_f32_16x16x32_bf16 v[78:81], v[158:161], v[198:201], v[78:81]
	v_mfma_f32_16x16x32_bf16 v[74:77], v[166:169], v[198:201], v[74:77]
	s_barrier
	s_add_i32 s88, 0, 0x14000
	s_add_i32 s86, s86, s69
	s_add_u32 s98, s58, s22
	s_addc_u32 s99, s59, s23
	s_mov_b32 m0, s86
	ds_read_b128 v[208:211], v202 offset:16384
	ds_read_b128 v[212:215], v202 offset:17408
	ds_read_b128 v[216:219], v202 offset:18432
	ds_read_b128 v[220:223], v202 offset:19456
	global_load_lds_dwordx4 v0, s[58:59]
	s_add_i32 m0, s86, 0x2000
	s_nop 0
	global_load_lds_dwordx4 v130, s[58:59]
	s_barrier
	s_waitcnt lgkmcnt(0)
	v_mfma_f32_16x16x32_bf16 v[118:121], v[208:211], v[170:173], v[118:121]
	v_mfma_f32_16x16x32_bf16 v[114:117], v[216:219], v[170:173], v[114:117]
	v_mfma_f32_16x16x32_bf16 v[102:105], v[208:211], v[178:181], v[102:105]
	v_mfma_f32_16x16x32_bf16 v[98:101], v[216:219], v[178:181], v[98:101]
	v_mfma_f32_16x16x32_bf16 v[86:89], v[208:211], v[186:189], v[86:89]
	v_mfma_f32_16x16x32_bf16 v[82:85], v[216:219], v[186:189], v[82:85]
	v_mfma_f32_16x16x32_bf16 v[70:73], v[208:211], v[194:197], v[70:73]
	v_mfma_f32_16x16x32_bf16 v[66:69], v[216:219], v[194:197], v[66:69]
	v_mfma_f32_16x16x32_bf16 v[118:121], v[212:215], v[174:177], v[118:121]
	v_mfma_f32_16x16x32_bf16 v[114:117], v[220:223], v[174:177], v[114:117]
	v_mfma_f32_16x16x32_bf16 v[102:105], v[212:215], v[182:185], v[102:105]
	v_mfma_f32_16x16x32_bf16 v[98:101], v[220:223], v[182:185], v[98:101]
	v_mfma_f32_16x16x32_bf16 v[86:89], v[212:215], v[190:193], v[86:89]
	v_mfma_f32_16x16x32_bf16 v[82:85], v[220:223], v[190:193], v[82:85]
	v_mfma_f32_16x16x32_bf16 v[70:73], v[212:215], v[198:201], v[70:73]
	v_mfma_f32_16x16x32_bf16 v[66:69], v[220:223], v[198:201], v[66:69]
	s_mov_b32 m0, s55
	s_add_u32 s100, s60, s22
	s_addc_u32 s101, s61, s23
	s_barrier
	ds_read_b128 v[170:173], v151 offset:16384
	ds_read_b128 v[174:177], v151 offset:17408
	ds_read_b128 v[178:181], v151 offset:18432
	ds_read_b128 v[182:185], v151 offset:19456
	ds_read_b128 v[186:189], v151 offset:20480
	ds_read_b128 v[190:193], v151 offset:21504
	ds_read_b128 v[194:197], v151 offset:22528
	ds_read_b128 v[198:201], v151 offset:23552
	global_load_lds_dwordx4 v134, s[60:61]
	s_mov_b32 m0, s72
	s_nop 0
	global_load_lds_dwordx4 v132, s[60:61]
	s_waitcnt vmcnt(10)
	s_barrier
	s_waitcnt lgkmcnt(0)
	v_mfma_f32_16x16x32_bf16 v[62:65], v[154:157], v[170:173], v[62:65]
	v_mfma_f32_16x16x32_bf16 v[58:61], v[162:165], v[170:173], v[58:61]
	v_mfma_f32_16x16x32_bf16 v[54:57], v[154:157], v[178:181], v[54:57]
	v_mfma_f32_16x16x32_bf16 v[46:49], v[162:165], v[178:181], v[46:49]
	v_mfma_f32_16x16x32_bf16 v[38:41], v[154:157], v[186:189], v[38:41]
	v_mfma_f32_16x16x32_bf16 v[30:33], v[162:165], v[186:189], v[30:33]
	v_mfma_f32_16x16x32_bf16 v[22:25], v[154:157], v[194:197], v[22:25]
	v_mfma_f32_16x16x32_bf16 v[14:17], v[162:165], v[194:197], v[14:17]
	v_mfma_f32_16x16x32_bf16 v[62:65], v[158:161], v[174:177], v[62:65]
	v_mfma_f32_16x16x32_bf16 v[58:61], v[166:169], v[174:177], v[58:61]
	v_mfma_f32_16x16x32_bf16 v[54:57], v[158:161], v[182:185], v[54:57]
	v_mfma_f32_16x16x32_bf16 v[46:49], v[166:169], v[182:185], v[46:49]
	v_mfma_f32_16x16x32_bf16 v[38:41], v[158:161], v[190:193], v[38:41]
	v_mfma_f32_16x16x32_bf16 v[30:33], v[166:169], v[190:193], v[30:33]
	v_mfma_f32_16x16x32_bf16 v[22:25], v[158:161], v[198:201], v[22:25]
	v_mfma_f32_16x16x32_bf16 v[14:17], v[166:169], v[198:201], v[14:17]
	s_barrier
	ds_read_b128 v[154:157], v202 offset:32768
	ds_read_b128 v[158:161], v202 offset:33792
	ds_read_b128 v[162:165], v202 offset:34816
	ds_read_b128 v[166:169], v202 offset:35840
	s_add_u32 s86, s58, 0x80000
	s_addc_u32 s87, s59, 0
	s_add_i32 s88, s88, s69
	s_mov_b32 m0, s88
	s_nop 0
	global_load_lds_dwordx4 v0, s[86:87]
	s_add_i32 m0, s88, 0x2000
	s_nop 0
	global_load_lds_dwordx4 v130, s[86:87]
	s_waitcnt vmcnt(6)
	s_barrier
; #define PG8_STAGE(bufoff, gbase, voff) do { _Pragma("unroll") for (int _i = 0; _i < 2; ++_i) \
;         __builtin_amdgcn_global_load_lds((const unsigned*)((const char*)(gbase) + (voff)[_i]), (LAS unsigned*)(lds + (bufoff) + ldsw + _i * 8192), 16, 0, 0); } while (0)
; #define PG8_LDA(dst, b, h) do { _Pragma("unroll") for (int m = 0; m < 4; ++m) _Pragma("unroll") for (int k = 0; k < 2; ++k) dst[m][k] = *(const LAS bf16x8*)(lds + PG8_SA(b, h) + aoff + m * 2048 + k * 1024); } while (0)
; #define PG8_LDB(dst, b, h) do { _Pragma("unroll") for (int n = 0; n < 2; ++n) _Pragma("unroll") for (int k = 0; k < 2; ++k) dst[n][k] = *(const LAS bf16x8*)(lds + PG8_SB(b, h) + boff + n * 2048 + k * 1024); } while (0)
; #define PG8_MMA(ai, bj, At, Bt) do { __builtin_amdgcn_s_setprio(1); _Pragma("unroll") for (int m = 0; m < 4; ++m) _Pragma("unroll") for (int n = 0; n < 2; ++n) _Pragma("unroll") for (int k = 0; k < 2; ++k) \
;         acc[ai][bj][m][n] = __builtin_amdgcn_mfma_f32_16x16x32_bf16(Bt[n][k], At[m][k], acc[ai][bj][m][n], 0, 0, 0); __builtin_amdgcn_s_setprio(0); } while (0)
; #define PG8_WAIT_V(n) asm volatile("s_waitcnt vmcnt(" #n ")" ::: "memory")
; #define PG8_WAIT_L(n) asm volatile("s_waitcnt lgkmcnt(" #n ")" ::: "memory")
; #define PG8_BAR __builtin_amdgcn_s_barrier()
; #define PG8_SCHED __builtin_amdgcn_sched_barrier(0)
; template <class Epi>
; __device__ __forceinline__ void gemm_phase(LAS unsigned char* lds, const Gemm g, const StaticOrder& S, const Epi& E) {
;     ...
;             PG8_WAIT_V(6); PG8_BAR; PG8_MMA(1, 1, At, B1); PG8_BAR;
;             PG8_LDB(B0, 1, 0); PG8_SCHED; PG8_LDA(At, 1, 0); PG8_STAGE(PG8_SA(0, 1), a2 + hstep, voffA);
;             PG8_WAIT_L(8); PG8_BAR; PG8_WAIT_L(0); PG8_MMA(0, 0, At, B0); PG8_BAR; PG8_SCHED;
;             PG8_LDB(B1, 1, 1); PG8_STAGE(PG8_SB(1, 0), b3, voffB);
;             PG8_BAR; PG8_WAIT_L(0); PG8_MMA(0, 1, At, B1); PG8_BAR;
;             PG8_LDA(At, 1, 1); PG8_STAGE(PG8_SA(1, 0), a3, voffA);
;             PG8_BAR; PG8_WAIT_L(0); PG8_MMA(1, 0, At, B0); PG8_BAR; PG8_SCHED;
;             PG8_STAGE(PG8_SB(1, 1), b3 + hstep, voffB);
;             PG8_WAIT_V(6); PG8_BAR; PG8_MMA(1, 1, At, B1); PG8_BAR;
	v_mfma_f32_16x16x32_bf16 v[50:53], v[208:211], v[170:173], v[50:53]
	v_mfma_f32_16x16x32_bf16 v[42:45], v[216:219], v[170:173], v[42:45]
	v_mfma_f32_16x16x32_bf16 v[34:37], v[208:211], v[178:181], v[34:37]
	v_mfma_f32_16x16x32_bf16 v[26:29], v[216:219], v[178:181], v[26:29]
	v_mfma_f32_16x16x32_bf16 v[18:21], v[208:211], v[186:189], v[18:21]
	v_mfma_f32_16x16x32_bf16 v[10:13], v[216:219], v[186:189], v[10:13]
	v_mfma_f32_16x16x32_bf16 v[6:9], v[208:211], v[194:197], v[6:9]
	v_mfma_f32_16x16x32_bf16 v[2:5], v[216:219], v[194:197], v[2:5]
	v_mfma_f32_16x16x32_bf16 v[50:53], v[212:215], v[174:177], v[50:53]
	v_mfma_f32_16x16x32_bf16 v[42:45], v[220:223], v[174:177], v[42:45]
	v_mfma_f32_16x16x32_bf16 v[34:37], v[212:215], v[182:185], v[34:37]
	v_mfma_f32_16x16x32_bf16 v[26:29], v[220:223], v[182:185], v[26:29]
	v_mfma_f32_16x16x32_bf16 v[18:21], v[212:215], v[190:193], v[18:21]
	v_mfma_f32_16x16x32_bf16 v[10:13], v[220:223], v[190:193], v[10:13]
	v_mfma_f32_16x16x32_bf16 v[6:9], v[212:215], v[198:201], v[6:9]
	v_mfma_f32_16x16x32_bf16 v[2:5], v[220:223], v[198:201], v[2:5]
	s_add_i32 s86, 0, 0x18000
	s_barrier
	s_add_u32 s60, s60, 0x80000
	s_addc_u32 s61, s61, 0
	s_mov_b32 m0, s73
	ds_read_b128 v[170:173], v151 offset:32768
	ds_read_b128 v[174:177], v151 offset:33792
	ds_read_b128 v[178:181], v151 offset:34816
	ds_read_b128 v[182:185], v151 offset:35840
	ds_read_b128 v[186:189], v151 offset:36864
	ds_read_b128 v[190:193], v151 offset:37888
	ds_read_b128 v[194:197], v151 offset:38912
	ds_read_b128 v[198:201], v151 offset:39936
	global_load_lds_dwordx4 v134, s[60:61]
	s_mov_b32 m0, s74
	s_nop 0
	global_load_lds_dwordx4 v132, s[60:61]
	s_waitcnt lgkmcnt(8)
	s_barrier
	s_waitcnt lgkmcnt(0)
	v_mfma_f32_16x16x32_bf16 v[126:129], v[154:157], v[170:173], v[126:129]
	v_mfma_f32_16x16x32_bf16 v[122:125], v[162:165], v[170:173], v[122:125]
	v_mfma_f32_16x16x32_bf16 v[110:113], v[154:157], v[178:181], v[110:113]
	v_mfma_f32_16x16x32_bf16 v[106:109], v[162:165], v[178:181], v[106:109]
	v_mfma_f32_16x16x32_bf16 v[94:97], v[154:157], v[186:189], v[94:97]
	v_mfma_f32_16x16x32_bf16 v[90:93], v[162:165], v[186:189], v[90:93]
	v_mfma_f32_16x16x32_bf16 v[78:81], v[154:157], v[194:197], v[78:81]
	v_mfma_f32_16x16x32_bf16 v[74:77], v[162:165], v[194:197], v[74:77]
	v_mfma_f32_16x16x32_bf16 v[126:129], v[158:161], v[174:177], v[126:129]
	v_mfma_f32_16x16x32_bf16 v[122:125], v[166:169], v[174:177], v[122:125]
	v_mfma_f32_16x16x32_bf16 v[110:113], v[158:161], v[182:185], v[110:113]
	v_mfma_f32_16x16x32_bf16 v[106:109], v[166:169], v[182:185], v[106:109]
	v_mfma_f32_16x16x32_bf16 v[94:97], v[158:161], v[190:193], v[94:97]
	v_mfma_f32_16x16x32_bf16 v[90:93], v[166:169], v[190:193], v[90:93]
	v_mfma_f32_16x16x32_bf16 v[78:81], v[158:161], v[198:201], v[78:81]
	v_mfma_f32_16x16x32_bf16 v[74:77], v[166:169], v[198:201], v[74:77]
	s_barrier
	s_add_i32 s60, 0, 0x1c000
	s_add_i32 s61, s86, s69
	s_mov_b32 m0, s61
	ds_read_b128 v[208:211], v202 offset:49152
	ds_read_b128 v[212:215], v202 offset:50176
	ds_read_b128 v[216:219], v202 offset:51200
	ds_read_b128 v[220:223], v202 offset:52224
	global_load_lds_dwordx4 v0, s[98:99]
	s_add_i32 m0, s61, 0x2000
	s_nop 0
	global_load_lds_dwordx4 v130, s[98:99]
	s_barrier
	s_waitcnt lgkmcnt(0)
	v_mfma_f32_16x16x32_bf16 v[118:121], v[208:211], v[170:173], v[118:121]
	v_mfma_f32_16x16x32_bf16 v[114:117], v[216:219], v[170:173], v[114:117]
	v_mfma_f32_16x16x32_bf16 v[102:105], v[208:211], v[178:181], v[102:105]
	v_mfma_f32_16x16x32_bf16 v[98:101], v[216:219], v[178:181], v[98:101]
	v_mfma_f32_16x16x32_bf16 v[86:89], v[208:211], v[186:189], v[86:89]
	v_mfma_f32_16x16x32_bf16 v[82:85], v[216:219], v[186:189], v[82:85]
	v_mfma_f32_16x16x32_bf16 v[70:73], v[208:211], v[194:197], v[70:73]
	v_mfma_f32_16x16x32_bf16 v[66:69], v[216:219], v[194:197], v[66:69]
	v_mfma_f32_16x16x32_bf16 v[118:121], v[212:215], v[174:177], v[118:121]
	v_mfma_f32_16x16x32_bf16 v[114:117], v[220:223], v[174:177], v[114:117]
	v_mfma_f32_16x16x32_bf16 v[102:105], v[212:215], v[182:185], v[102:105]
	v_mfma_f32_16x16x32_bf16 v[98:101], v[220:223], v[182:185], v[98:101]
	v_mfma_f32_16x16x32_bf16 v[86:89], v[212:215], v[190:193], v[86:89]
	v_mfma_f32_16x16x32_bf16 v[82:85], v[220:223], v[190:193], v[82:85]
	v_mfma_f32_16x16x32_bf16 v[70:73], v[212:215], v[198:201], v[70:73]
	v_mfma_f32_16x16x32_bf16 v[66:69], v[220:223], v[198:201], v[66:69]
	s_mov_b32 m0, s76
	s_barrier
	ds_read_b128 v[170:173], v151 offset:49152
	ds_read_b128 v[174:177], v151 offset:50176
	ds_read_b128 v[178:181], v151 offset:51200
	ds_read_b128 v[182:185], v151 offset:52224
	ds_read_b128 v[186:189], v151 offset:53248
	ds_read_b128 v[190:193], v151 offset:54272
	ds_read_b128 v[194:197], v151 offset:55296
	ds_read_b128 v[198:201], v151 offset:56320
	global_load_lds_dwordx4 v134, s[100:101]
	s_mov_b32 m0, s77
	s_nop 0
	global_load_lds_dwordx4 v132, s[100:101]
	s_waitcnt vmcnt(10)
	s_barrier
	s_waitcnt lgkmcnt(0)
	v_mfma_f32_16x16x32_bf16 v[62:65], v[154:157], v[170:173], v[62:65]
	v_mfma_f32_16x16x32_bf16 v[58:61], v[162:165], v[170:173], v[58:61]
	v_mfma_f32_16x16x32_bf16 v[54:57], v[154:157], v[178:181], v[54:57]
	v_mfma_f32_16x16x32_bf16 v[46:49], v[162:165], v[178:181], v[46:49]
	v_mfma_f32_16x16x32_bf16 v[38:41], v[154:157], v[186:189], v[38:41]
	v_mfma_f32_16x16x32_bf16 v[30:33], v[162:165], v[186:189], v[30:33]
	v_mfma_f32_16x16x32_bf16 v[22:25], v[154:157], v[194:197], v[22:25]
	v_mfma_f32_16x16x32_bf16 v[14:17], v[162:165], v[194:197], v[14:17]
	v_mfma_f32_16x16x32_bf16 v[62:65], v[158:161], v[174:177], v[62:65]
	v_mfma_f32_16x16x32_bf16 v[58:61], v[166:169], v[174:177], v[58:61]
	v_mfma_f32_16x16x32_bf16 v[54:57], v[158:161], v[182:185], v[54:57]
	v_mfma_f32_16x16x32_bf16 v[46:49], v[166:169], v[182:185], v[46:49]
	v_mfma_f32_16x16x32_bf16 v[38:41], v[158:161], v[190:193], v[38:41]
	v_mfma_f32_16x16x32_bf16 v[30:33], v[166:169], v[190:193], v[30:33]
	v_mfma_f32_16x16x32_bf16 v[22:25], v[158:161], v[198:201], v[22:25]
	v_mfma_f32_16x16x32_bf16 v[14:17], v[166:169], v[198:201], v[14:17]
	s_barrier
; __device__ __forceinline__ unsigned pk2(float lo, float hi) { f32x2 v = {lo, hi}; bf16x2_t b = __builtin_convertvector(v, bf16x2_t); return __builtin_bit_cast(unsigned, b); }
; #define PG8_STAGE(bufoff, gbase, voff) do { _Pragma("unroll") for (int _i = 0; _i < 2; ++_i) \
;         __builtin_amdgcn_global_load_lds((const unsigned*)((const char*)(gbase) + (voff)[_i]), (LAS unsigned*)(lds + (bufoff) + ldsw + _i * 8192), 16, 0, 0); } while (0)
; #define PG8_WAIT_V(n) asm volatile("s_waitcnt vmcnt(" #n ")" ::: "memory")
; #define PG8_WAIT_L(n) asm volatile("s_waitcnt lgkmcnt(" #n ")" ::: "memory")
; #define PG8_BAR __builtin_amdgcn_s_barrier()
;     __device__ __forceinline__ void operator()(const AccT& acc, const Unit& u, int wr, int wc, int fr, int fq) const {
;         const int row0 = u.pm * BM + wr * 64 + fr, col0 = u.pn * BM + wc * 32 + 8 * fq;
;         float rsv[8];
;         if (ss) {
;             const int ln = (fq << 4) | fr;
;             float sa = ss[u.pm * BM + wr * 64 + ln], sb = ss[u.pm * BM + HALF + wr * 64 + ln];
;             sa = __builtin_amdgcn_rsqf(sa * (1.0f / DM) + EPS); sb = __builtin_amdgcn_rsqf(sb * (1.0f / DM) + EPS);
; #pragma unroll
;             for (int m = 0; m < 4; ++m) { rsv[m] = __shfl(sa, 16 * m + fr); rsv[4 + m] = __shfl(sb, 16 * m + fr); }
;         } else {
; #pragma unroll
;             for (int i = 0; i < 8; ++i) rsv[i] = 1.0f;
;         }
; #pragma unroll
;         for (int ai = 0; ai < 2; ++ai)
; #pragma unroll
;             for (int m = 0; m < 4; ++m) {
;                 const int row = row0 + ai * HALF + m * 16;
;                 const float rs = rsv[ai * 4 + m];
; #pragma unroll
;                 for (int bj = 0; bj < 2; ++bj) {
;                     const f32x4 v0 = acc[ai][bj][m][0] * rs, v1 = acc[ai][bj][m][1] * rs;
;                     u32x4 w; w.x = pk2(v0[0], v0[1]); w.y = pk2(v0[2], v0[3]); w.z = pk2(v1[0], v1[1]); w.w = pk2(v1[2], v1[3]);
;                     *(u32x4*)(out + (size_t)row * ldo + col0 + bj * HALF) = w;
;                 }
; template <class Epi>
; __device__ __forceinline__ void gemm_phase(LAS unsigned char* lds, const Gemm g, const StaticOrder& S, const Epi& E) {
;     ...
;             PG8_BAR; PG8_WAIT_L(0); PG8_MMA(1, 0, At, B0); PG8_BAR; PG8_SCHED;
;             PG8_STAGE(PG8_SB(1, 1), b3 + hstep, voffB);
;             PG8_WAIT_V(6); PG8_BAR; PG8_MMA(1, 1, At, B1); PG8_BAR;
	ds_read_b128 v[154:157], v202
	ds_read_b128 v[158:161], v202 offset:1024
	ds_read_b128 v[162:165], v202 offset:2048
	ds_read_b128 v[166:169], v202 offset:3072
	s_add_u32 s58, s58, 0x80080
	s_addc_u32 s59, s59, 0
	s_add_i32 s60, s60, s69
	s_mov_b32 m0, s60
	s_nop 0
	global_load_lds_dwordx4 v0, s[58:59]
	s_add_i32 m0, s60, 0x2000
	s_nop 0
	global_load_lds_dwordx4 v130, s[58:59]
	s_waitcnt vmcnt(6)
	s_barrier
	v_mfma_f32_16x16x32_bf16 v[50:53], v[208:211], v[170:173], v[50:53]
	v_mfma_f32_16x16x32_bf16 v[42:45], v[216:219], v[170:173], v[42:45]
	v_mfma_f32_16x16x32_bf16 v[34:37], v[208:211], v[178:181], v[34:37]
	v_mfma_f32_16x16x32_bf16 v[26:29], v[216:219], v[178:181], v[26:29]
	v_mfma_f32_16x16x32_bf16 v[18:21], v[208:211], v[186:189], v[18:21]
	v_mfma_f32_16x16x32_bf16 v[10:13], v[216:219], v[186:189], v[10:13]
	v_mfma_f32_16x16x32_bf16 v[6:9], v[208:211], v[194:197], v[6:9]
	v_mfma_f32_16x16x32_bf16 v[2:5], v[216:219], v[194:197], v[2:5]
	v_mfma_f32_16x16x32_bf16 v[50:53], v[212:215], v[174:177], v[50:53]
	v_mfma_f32_16x16x32_bf16 v[42:45], v[220:223], v[174:177], v[42:45]
	v_mfma_f32_16x16x32_bf16 v[34:37], v[212:215], v[182:185], v[34:37]
	v_mfma_f32_16x16x32_bf16 v[26:29], v[220:223], v[182:185], v[26:29]
	v_mfma_f32_16x16x32_bf16 v[18:21], v[212:215], v[190:193], v[18:21]
	v_mfma_f32_16x16x32_bf16 v[10:13], v[220:223], v[190:193], v[10:13]
	v_mfma_f32_16x16x32_bf16 v[6:9], v[212:215], v[198:201], v[6:9]
	v_mfma_f32_16x16x32_bf16 v[2:5], v[220:223], v[198:201], v[2:5]
	s_add_i32 s85, s85, 2
	s_add_u32 s56, s56, 0x100
	s_addc_u32 s57, s57, 0
	s_add_u32 s83, s83, 0x100
	s_addc_u32 s84, s84, 0
	s_cmp_gt_u32 s85, 29
	s_barrier
	s_cbranch_scc0 .LBB0_64
	s_waitcnt lgkmcnt(0)
	s_lshl_b32 s47, s54, 8
	s_add_i32 s47, s47, s75
	v_or_b32_e32 v154, s47, v145
	v_ashrrev_i32_e32 v155, 31, v154
	v_lshl_add_u64 v[154:155], v[154:155], 2, s[2:3]
	global_load_dword v140, v[154:155], off
	v_add_u32_e32 v154, s47, v147
	v_ashrrev_i32_e32 v155, 31, v154
	v_lshl_add_u64 v[154:155], v[154:155], 2, s[2:3]
	global_load_dword v142, v[154:155], off
	v_lshl_or_b32 v158, s80, 8, v149
	v_ashrrev_i32_e32 v159, 31, v158
	s_and_b64 vcc, exec, s[36:37]
	s_mov_b32 s80, s46
	s_mov_b32 s54, s48
	s_mov_b64 s[58:59], s[52:53]
	s_waitcnt vmcnt(0)
	v_fmamk_f32 v140, v140, 0x3a000000, v233
	v_rsq_f32_e32 v140, v140
	v_fmamk_f32 v142, v142, 0x3a000000, v233
	ds_bpermute_b32 v154, v152, v140
	v_rsq_f32_e32 v153, v142
	ds_bpermute_b32 v156, v152, v140 offset:64
	ds_bpermute_b32 v150, v152, v140 offset:128
	ds_bpermute_b32 v148, v152, v140 offset:192
	ds_bpermute_b32 v146, v152, v153
	ds_bpermute_b32 v144, v152, v153 offset:64
	ds_bpermute_b32 v142, v152, v153 offset:128
	ds_bpermute_b32 v140, v152, v153 offset:192
	v_or_b32_e32 v153, s47, v141
	s_waitcnt lgkmcnt(0)
	v_pk_mul_f32 v[126:127], v[126:127], v[154:155] op_sel_hi:[1,0]
	v_pk_mul_f32 v[122:123], v[122:123], v[154:155] op_sel_hi:[1,0]
	v_pk_mul_f32 v[128:129], v[128:129], v[154:155] op_sel_hi:[1,0]
	v_pk_mul_f32 v[160:161], v[124:125], v[154:155] op_sel_hi:[1,0]
	v_cvt_pk_bf16_f32 v124, v126, v127
	v_cvt_pk_bf16_f32 v126, v122, v123
	v_mad_i64_i32 v[122:123], s[56:57], v153, s63, 0
	v_cvt_pk_bf16_f32 v125, v128, v129
	v_lshl_add_u64 v[128:129], v[122:123], 1, s[44:45]
	v_lshlrev_b64 v[122:123], 1, v[158:159]
	v_cvt_pk_bf16_f32 v127, v160, v161
	v_lshl_add_u64 v[128:129], v[128:129], 0, v[122:123]
	global_store_dwordx4 v[128:129], v[124:127], off
	v_pk_mul_f32 v[120:121], v[120:121], v[154:155] op_sel_hi:[1,0]
	v_pk_mul_f32 v[118:119], v[118:119], v[154:155] op_sel_hi:[1,0]
	v_pk_mul_f32 v[124:125], v[116:117], v[154:155] op_sel_hi:[1,0]
	v_pk_mul_f32 v[116:117], v[114:115], v[154:155] op_sel_hi:[1,0]
	v_cvt_pk_bf16_f32 v114, v118, v119
	v_cvt_pk_bf16_f32 v115, v120, v121
	v_cvt_pk_bf16_f32 v116, v116, v117
	v_cvt_pk_bf16_f32 v117, v124, v125
	global_store_dwordx4 v[128:129], v[114:117], off offset:256
	v_pk_mul_f32 v[110:111], v[110:111], v[156:157] op_sel_hi:[1,0]
	v_pk_mul_f32 v[112:113], v[112:113], v[156:157] op_sel_hi:[1,0]
	v_or_b32_e32 v116, 16, v153
	v_pk_mul_f32 v[114:115], v[108:109], v[156:157] op_sel_hi:[1,0]
	v_pk_mul_f32 v[108:109], v[106:107], v[156:157] op_sel_hi:[1,0]
	v_cvt_pk_bf16_f32 v106, v110, v111
	v_mad_i64_i32 v[110:111], s[56:57], v116, s63, 0
	v_lshl_add_u64 v[110:111], v[110:111], 1, s[44:45]
	v_cvt_pk_bf16_f32 v107, v112, v113
	v_cvt_pk_bf16_f32 v108, v108, v109
	v_cvt_pk_bf16_f32 v109, v114, v115
	v_lshl_add_u64 v[110:111], v[110:111], 0, v[122:123]
	global_store_dwordx4 v[110:111], v[106:109], off
	v_pk_mul_f32 v[104:105], v[104:105], v[156:157] op_sel_hi:[1,0]
	v_pk_mul_f32 v[102:103], v[102:103], v[156:157] op_sel_hi:[1,0]
	v_pk_mul_f32 v[106:107], v[100:101], v[156:157] op_sel_hi:[1,0]
	v_pk_mul_f32 v[100:101], v[98:99], v[156:157] op_sel_hi:[1,0]
	v_cvt_pk_bf16_f32 v98, v102, v103
	v_cvt_pk_bf16_f32 v99, v104, v105
	v_cvt_pk_bf16_f32 v100, v100, v101
	v_cvt_pk_bf16_f32 v101, v106, v107
	global_store_dwordx4 v[110:111], v[98:101], off offset:256
	v_pk_mul_f32 v[94:95], v[94:95], v[150:151] op_sel_hi:[1,0]
	v_pk_mul_f32 v[96:97], v[96:97], v[150:151] op_sel_hi:[1,0]
	v_or_b32_e32 v100, 32, v153
	v_pk_mul_f32 v[98:99], v[92:93], v[150:151] op_sel_hi:[1,0]
	v_pk_mul_f32 v[92:93], v[90:91], v[150:151] op_sel_hi:[1,0]
	v_cvt_pk_bf16_f32 v90, v94, v95
	v_mad_i64_i32 v[94:95], s[56:57], v100, s63, 0
	v_lshl_add_u64 v[94:95], v[94:95], 1, s[44:45]
	v_cvt_pk_bf16_f32 v91, v96, v97
	v_cvt_pk_bf16_f32 v92, v92, v93
	v_cvt_pk_bf16_f32 v93, v98, v99
	v_lshl_add_u64 v[94:95], v[94:95], 0, v[122:123]
	global_store_dwordx4 v[94:95], v[90:93], off
	v_pk_mul_f32 v[88:89], v[88:89], v[150:151] op_sel_hi:[1,0]
; __device__ __forceinline__ unsigned pk2(float lo, float hi) { f32x2 v = {lo, hi}; bf16x2_t b = __builtin_convertvector(v, bf16x2_t); return __builtin_bit_cast(unsigned, b); }
; #define PG8_WAIT_V(n) asm volatile("s_waitcnt vmcnt(" #n ")" ::: "memory")
; #define PG8_BAR __builtin_amdgcn_s_barrier()
;     __device__ __forceinline__ void operator()(const AccT& acc, const Unit& u, int wr, int wc, int fr, int fq) const {
;     ...
; #pragma unroll
;         for (int ai = 0; ai < 2; ++ai)
; #pragma unroll
;             for (int m = 0; m < 4; ++m) {
;                 const int row = row0 + ai * HALF + m * 16;
;                 const float rs = rsv[ai * 4 + m];
; #pragma unroll
;                 for (int bj = 0; bj < 2; ++bj) {
;                     const f32x4 v0 = acc[ai][bj][m][0] * rs, v1 = acc[ai][bj][m][1] * rs;
;                     u32x4 w; w.x = pk2(v0[0], v0[1]); w.y = pk2(v0[2], v0[3]); w.z = pk2(v1[0], v1[1]); w.w = pk2(v1[2], v1[3]);
;                     *(u32x4*)(out + (size_t)row * ldo + col0 + bj * HALF) = w;
;                 }
; template <class Epi>
; __device__ __forceinline__ void gemm_phase(LAS unsigned char* lds, const Gemm g, const StaticOrder& S, const Epi& E) {
;     ...
;         E(acc, cur, wr, wc, fr, fq);
;         if (!has_next) break;
; #pragma unroll
;         for (int a = 0; a < 2; ++a)
; #pragma unroll
;             for (int b = 0; b < 2; ++b)
; #pragma unroll
;                 for (int m = 0; m < 4; ++m)
; #pragma unroll
;                     for (int n = 0; n < 2; ++n) acc[a][b][m][n] = (f32x4){0.f, 0.f, 0.f, 0.f};
;         cur = nxt; cA = nA; cB = nB; ++ui;
;     }
;     PG8_WAIT_V(0);
;     if (wr == 0) PG8_BAR;
;     PG8_BAR;
	v_pk_mul_f32 v[86:87], v[86:87], v[150:151] op_sel_hi:[1,0]
	v_pk_mul_f32 v[90:91], v[84:85], v[150:151] op_sel_hi:[1,0]
	v_pk_mul_f32 v[84:85], v[82:83], v[150:151] op_sel_hi:[1,0]
	v_cvt_pk_bf16_f32 v82, v86, v87
	v_cvt_pk_bf16_f32 v83, v88, v89
	v_cvt_pk_bf16_f32 v84, v84, v85
	v_cvt_pk_bf16_f32 v85, v90, v91
	global_store_dwordx4 v[94:95], v[82:85], off offset:256
	v_pk_mul_f32 v[78:79], v[78:79], v[148:149] op_sel_hi:[1,0]
	v_pk_mul_f32 v[80:81], v[80:81], v[148:149] op_sel_hi:[1,0]
	v_or_b32_e32 v84, 48, v153
	v_pk_mul_f32 v[82:83], v[76:77], v[148:149] op_sel_hi:[1,0]
	v_pk_mul_f32 v[76:77], v[74:75], v[148:149] op_sel_hi:[1,0]
	v_cvt_pk_bf16_f32 v74, v78, v79
	v_mad_i64_i32 v[78:79], s[56:57], v84, s63, 0
	v_lshl_add_u64 v[78:79], v[78:79], 1, s[44:45]
	v_cvt_pk_bf16_f32 v75, v80, v81
	v_cvt_pk_bf16_f32 v76, v76, v77
	v_cvt_pk_bf16_f32 v77, v82, v83
	v_lshl_add_u64 v[78:79], v[78:79], 0, v[122:123]
	global_store_dwordx4 v[78:79], v[74:77], off
	v_pk_mul_f32 v[72:73], v[72:73], v[148:149] op_sel_hi:[1,0]
	v_pk_mul_f32 v[70:71], v[70:71], v[148:149] op_sel_hi:[1,0]
	v_pk_mul_f32 v[74:75], v[68:69], v[148:149] op_sel_hi:[1,0]
	v_pk_mul_f32 v[68:69], v[66:67], v[148:149] op_sel_hi:[1,0]
	v_cvt_pk_bf16_f32 v66, v70, v71
	v_cvt_pk_bf16_f32 v67, v72, v73
	v_cvt_pk_bf16_f32 v68, v68, v69
	v_cvt_pk_bf16_f32 v69, v74, v75
	global_store_dwordx4 v[78:79], v[66:69], off offset:256
	v_pk_mul_f32 v[62:63], v[62:63], v[146:147] op_sel_hi:[1,0]
	v_pk_mul_f32 v[64:65], v[64:65], v[146:147] op_sel_hi:[1,0]
	v_add_u32_e32 v68, 0x80, v153
	v_pk_mul_f32 v[66:67], v[60:61], v[146:147] op_sel_hi:[1,0]
	v_pk_mul_f32 v[60:61], v[58:59], v[146:147] op_sel_hi:[1,0]
	v_cvt_pk_bf16_f32 v58, v62, v63
	v_mad_i64_i32 v[62:63], s[56:57], v68, s63, 0
	v_lshl_add_u64 v[62:63], v[62:63], 1, s[44:45]
	v_cvt_pk_bf16_f32 v59, v64, v65
	v_cvt_pk_bf16_f32 v60, v60, v61
	v_cvt_pk_bf16_f32 v61, v66, v67
	v_lshl_add_u64 v[62:63], v[62:63], 0, v[122:123]
	global_store_dwordx4 v[62:63], v[58:61], off
	v_pk_mul_f32 v[52:53], v[52:53], v[146:147] op_sel_hi:[1,0]
	v_pk_mul_f32 v[50:51], v[50:51], v[146:147] op_sel_hi:[1,0]
	v_pk_mul_f32 v[58:59], v[44:45], v[146:147] op_sel_hi:[1,0]
	v_pk_mul_f32 v[44:45], v[42:43], v[146:147] op_sel_hi:[1,0]
	v_cvt_pk_bf16_f32 v42, v50, v51
	v_cvt_pk_bf16_f32 v43, v52, v53
	v_cvt_pk_bf16_f32 v44, v44, v45
	v_cvt_pk_bf16_f32 v45, v58, v59
	global_store_dwordx4 v[62:63], v[42:45], off offset:256
	v_add_u32_e32 v50, 0x90, v153
	v_pk_mul_f32 v[46:47], v[46:47], v[144:145] op_sel_hi:[1,0]
	v_pk_mul_f32 v[44:45], v[56:57], v[144:145] op_sel_hi:[1,0]
	v_pk_mul_f32 v[42:43], v[54:55], v[144:145] op_sel_hi:[1,0]
	v_pk_mul_f32 v[48:49], v[48:49], v[144:145] op_sel_hi:[1,0]
	v_cvt_pk_bf16_f32 v42, v42, v43
	v_cvt_pk_bf16_f32 v43, v44, v45
	v_cvt_pk_bf16_f32 v44, v46, v47
	v_mad_i64_i32 v[46:47], s[56:57], v50, s63, 0
	v_lshl_add_u64 v[46:47], v[46:47], 1, s[44:45]
	v_cvt_pk_bf16_f32 v45, v48, v49
	v_lshl_add_u64 v[46:47], v[46:47], 0, v[122:123]
	global_store_dwordx4 v[46:47], v[42:45], off
	v_pk_mul_f32 v[36:37], v[36:37], v[144:145] op_sel_hi:[1,0]
	v_pk_mul_f32 v[34:35], v[34:35], v[144:145] op_sel_hi:[1,0]
	v_pk_mul_f32 v[42:43], v[28:29], v[144:145] op_sel_hi:[1,0]
	v_pk_mul_f32 v[28:29], v[26:27], v[144:145] op_sel_hi:[1,0]
	v_cvt_pk_bf16_f32 v26, v34, v35
	v_cvt_pk_bf16_f32 v27, v36, v37
	v_cvt_pk_bf16_f32 v28, v28, v29
	v_cvt_pk_bf16_f32 v29, v42, v43
	global_store_dwordx4 v[46:47], v[26:29], off offset:256
	v_add_u32_e32 v34, 0xa0, v153
	v_pk_mul_f32 v[30:31], v[30:31], v[142:143] op_sel_hi:[1,0]
	v_pk_mul_f32 v[28:29], v[40:41], v[142:143] op_sel_hi:[1,0]
	v_pk_mul_f32 v[26:27], v[38:39], v[142:143] op_sel_hi:[1,0]
	v_pk_mul_f32 v[32:33], v[32:33], v[142:143] op_sel_hi:[1,0]
	v_cvt_pk_bf16_f32 v26, v26, v27
	v_cvt_pk_bf16_f32 v27, v28, v29
	v_cvt_pk_bf16_f32 v28, v30, v31
	v_mad_i64_i32 v[30:31], s[56:57], v34, s63, 0
	v_lshl_add_u64 v[30:31], v[30:31], 1, s[44:45]
	v_cvt_pk_bf16_f32 v29, v32, v33
	v_lshl_add_u64 v[30:31], v[30:31], 0, v[122:123]
	global_store_dwordx4 v[30:31], v[26:29], off
	v_pk_mul_f32 v[20:21], v[20:21], v[142:143] op_sel_hi:[1,0]
	v_pk_mul_f32 v[18:19], v[18:19], v[142:143] op_sel_hi:[1,0]
	v_pk_mul_f32 v[26:27], v[12:13], v[142:143] op_sel_hi:[1,0]
	v_pk_mul_f32 v[12:13], v[10:11], v[142:143] op_sel_hi:[1,0]
	v_cvt_pk_bf16_f32 v10, v18, v19
	v_cvt_pk_bf16_f32 v11, v20, v21
	v_cvt_pk_bf16_f32 v12, v12, v13
	v_cvt_pk_bf16_f32 v13, v26, v27
	global_store_dwordx4 v[30:31], v[10:13], off offset:256
	v_add_u32_e32 v18, 0xb0, v153
	v_pk_mul_f32 v[14:15], v[14:15], v[140:141] op_sel_hi:[1,0]
	v_pk_mul_f32 v[12:13], v[24:25], v[140:141] op_sel_hi:[1,0]
	v_pk_mul_f32 v[10:11], v[22:23], v[140:141] op_sel_hi:[1,0]
	v_pk_mul_f32 v[16:17], v[16:17], v[140:141] op_sel_hi:[1,0]
	v_cvt_pk_bf16_f32 v10, v10, v11
	v_cvt_pk_bf16_f32 v11, v12, v13
	v_cvt_pk_bf16_f32 v12, v14, v15
	v_mad_i64_i32 v[14:15], s[56:57], v18, s63, 0
	v_lshl_add_u64 v[14:15], v[14:15], 1, s[44:45]
	v_cvt_pk_bf16_f32 v13, v16, v17
	v_lshl_add_u64 v[14:15], v[14:15], 0, v[122:123]
	global_store_dwordx4 v[14:15], v[10:13], off
	v_pk_mul_f32 v[8:9], v[8:9], v[140:141] op_sel_hi:[1,0]
	v_pk_mul_f32 v[6:7], v[6:7], v[140:141] op_sel_hi:[1,0]
	v_pk_mul_f32 v[10:11], v[4:5], v[140:141] op_sel_hi:[1,0]
	v_pk_mul_f32 v[4:5], v[2:3], v[140:141] op_sel_hi:[1,0]
	v_cvt_pk_bf16_f32 v2, v6, v7
	v_cvt_pk_bf16_f32 v3, v8, v9
	v_cvt_pk_bf16_f32 v4, v4, v5
	v_cvt_pk_bf16_f32 v5, v10, v11
	s_mov_b64 s[56:57], s[50:51]
	global_store_dwordx4 v[14:15], v[2:5], off offset:256
	s_cbranch_vccz .LBB0_61
	s_waitcnt vmcnt(0)
	s_cmpk_gt_u32 s64, 0xff
	s_cbranch_scc1 .LBB0_68
	s_barrier

; #define PG8_STAGE(bufoff, gbase, voff) do { _Pragma("unroll") for (int _i = 0; _i < 2; ++_i) \
;         __builtin_amdgcn_global_load_lds((const unsigned*)((const char*)(gbase) + (voff)[_i]), (LAS unsigned*)(lds + (bufoff) + ldsw + _i * 8192), 16, 0, 0); } while (0)
; #define PG8_LDA(dst, b, h) do { _Pragma("unroll") for (int m = 0; m < 4; ++m) _Pragma("unroll") for (int k = 0; k < 2; ++k) dst[m][k] = *(const LAS bf16x8*)(lds + PG8_SA(b, h) + aoff + m * 2048 + k * 1024); } while (0)
; #define PG8_LDB(dst, b, h) do { _Pragma("unroll") for (int n = 0; n < 2; ++n) _Pragma("unroll") for (int k = 0; k < 2; ++k) dst[n][k] = *(const LAS bf16x8*)(lds + PG8_SB(b, h) + boff + n * 2048 + k * 1024); } while (0)
; #define PG8_MMA(ai, bj, At, Bt) do { __builtin_amdgcn_s_setprio(1); _Pragma("unroll") for (int m = 0; m < 4; ++m) _Pragma("unroll") for (int n = 0; n < 2; ++n) _Pragma("unroll") for (int k = 0; k < 2; ++k) \
;         acc[ai][bj][m][n] = __builtin_amdgcn_mfma_f32_16x16x32_bf16(Bt[n][k], At[m][k], acc[ai][bj][m][n], 0, 0, 0); __builtin_amdgcn_s_setprio(0); } while (0)
; #define PG8_WAIT_V(n) asm volatile("s_waitcnt vmcnt(" #n ")" ::: "memory")
; #define PG8_WAIT_L(n) asm volatile("s_waitcnt lgkmcnt(" #n ")" ::: "memory")
; #define PG8_BAR __builtin_amdgcn_s_barrier()
; #define PG8_SCHED __builtin_amdgcn_sched_barrier(0)
; template <class Epi>
; __device__ __forceinline__ void gemm_phase(LAS unsigned char* lds, const Gemm g, const StaticOrder& S, const Epi& E) {
;     ...
;             PG8_LDB(B0, 0, 0); PG8_SCHED; PG8_LDA(At, 0, 0); PG8_STAGE(PG8_SA(1, 1), a1 + hstep, voffA);
;             PG8_WAIT_L(8); PG8_BAR; PG8_WAIT_L(0); PG8_MMA(0, 0, At, B0); PG8_BAR; PG8_SCHED;
;             PG8_LDB(B1, 0, 1); PG8_STAGE(PG8_SB(0, 0), b2, voffB);
;             PG8_BAR; PG8_WAIT_L(0); PG8_MMA(0, 1, At, B1); PG8_BAR;
;             PG8_LDA(At, 0, 1); PG8_STAGE(PG8_SA(0, 0), a2, voffA);
;             PG8_BAR; PG8_WAIT_L(0); PG8_MMA(1, 0, At, B0); PG8_BAR; PG8_SCHED;
;             PG8_STAGE(PG8_SB(0, 1), b2 + hstep, voffB);
;             PG8_WAIT_V(6); PG8_BAR; PG8_MMA(1, 1, At, B1); PG8_BAR;
;             PG8_LDB(B0, 1, 0); PG8_SCHED; PG8_LDA(At, 1, 0); PG8_STAGE(PG8_SA(0, 1), a2 + hstep, voffA);
;             PG8_WAIT_L(8); PG8_BAR; PG8_WAIT_L(0); PG8_MMA(0, 0, At, B0); PG8_BAR; PG8_SCHED;
.LBB0_77:
	s_add_u32 s56, s54, 0xfff80080
	s_addc_u32 s57, s55, -1
	s_add_i32 s81, 0, 0x10000
	s_cmp_eq_u32 s80, 28
	s_cselect_b32 s59, s49, s57
	s_cselect_b32 s58, s76, s56
	s_cselect_b32 s57, s47, s79
	s_cselect_b32 s56, s77, s78
	s_add_i32 m0, s65, 0xc000
	ds_read_b128 v[160:163], v143
	ds_read_b128 v[164:167], v143 offset:1024
	ds_read_b128 v[168:171], v143 offset:2048
	ds_read_b128 v[172:175], v143 offset:3072
	ds_read_b128 v[176:179], v143 offset:4096
	ds_read_b128 v[180:183], v143 offset:5120
	ds_read_b128 v[184:187], v143 offset:6144
	ds_read_b128 v[188:191], v143 offset:7168
	global_load_lds_dwordx4 v136, s[54:55]
	s_add_i32 m0, s65, 0xe000
	s_nop 0
	global_load_lds_dwordx4 v138, s[54:55]
	s_waitcnt lgkmcnt(8)
	s_barrier
	s_waitcnt lgkmcnt(0)
	v_mfma_f32_16x16x32_bf16 v[126:129], v[144:147], v[160:163], v[126:129]
	v_mfma_f32_16x16x32_bf16 v[122:125], v[152:155], v[160:163], v[122:125]
	v_mfma_f32_16x16x32_bf16 v[118:121], v[144:147], v[168:171], v[118:121]
	v_mfma_f32_16x16x32_bf16 v[114:117], v[152:155], v[168:171], v[114:117]
	v_mfma_f32_16x16x32_bf16 v[102:105], v[144:147], v[176:179], v[102:105]
	v_mfma_f32_16x16x32_bf16 v[98:101], v[152:155], v[176:179], v[98:101]
	v_mfma_f32_16x16x32_bf16 v[86:89], v[144:147], v[184:187], v[86:89]
	v_mfma_f32_16x16x32_bf16 v[82:85], v[152:155], v[184:187], v[82:85]
	v_mfma_f32_16x16x32_bf16 v[126:129], v[148:151], v[164:167], v[126:129]
	v_mfma_f32_16x16x32_bf16 v[122:125], v[156:159], v[164:167], v[122:125]
	v_mfma_f32_16x16x32_bf16 v[118:121], v[148:151], v[172:175], v[118:121]
	v_mfma_f32_16x16x32_bf16 v[114:117], v[156:159], v[172:175], v[114:117]
	v_mfma_f32_16x16x32_bf16 v[102:105], v[148:151], v[180:183], v[102:105]
	v_mfma_f32_16x16x32_bf16 v[98:101], v[156:159], v[180:183], v[98:101]
	v_mfma_f32_16x16x32_bf16 v[86:89], v[148:151], v[188:191], v[86:89]
	v_mfma_f32_16x16x32_bf16 v[82:85], v[156:159], v[188:191], v[82:85]
	s_barrier
	s_add_i32 s84, 0, 0x14000
	s_add_i32 s81, s81, s64
	ds_read_b128 v[192:195], v202 offset:16384
	ds_read_b128 v[196:199], v202 offset:17408
	ds_read_b128 v[208:211], v202 offset:18432
	ds_read_b128 v[212:215], v202 offset:19456
	s_mov_b32 m0, s81
	s_add_u32 s98, s56, s22
	s_addc_u32 s99, s57, s23
	global_load_lds_dwordx4 v0, s[56:57]
	s_add_i32 m0, s81, 0x2000
	s_nop 0
	global_load_lds_dwordx4 v130, s[56:57]
	s_barrier
	s_waitcnt lgkmcnt(0)
	v_mfma_f32_16x16x32_bf16 v[110:113], v[192:195], v[160:163], v[110:113]
	v_mfma_f32_16x16x32_bf16 v[106:109], v[208:211], v[160:163], v[106:109]
	v_mfma_f32_16x16x32_bf16 v[94:97], v[192:195], v[168:171], v[94:97]
	v_mfma_f32_16x16x32_bf16 v[90:93], v[208:211], v[168:171], v[90:93]
	v_mfma_f32_16x16x32_bf16 v[78:81], v[192:195], v[176:179], v[78:81]
	v_mfma_f32_16x16x32_bf16 v[74:77], v[208:211], v[176:179], v[74:77]
	v_mfma_f32_16x16x32_bf16 v[70:73], v[192:195], v[184:187], v[70:73]
	v_mfma_f32_16x16x32_bf16 v[66:69], v[208:211], v[184:187], v[66:69]
	v_mfma_f32_16x16x32_bf16 v[110:113], v[196:199], v[164:167], v[110:113]
	v_mfma_f32_16x16x32_bf16 v[106:109], v[212:215], v[164:167], v[106:109]
	v_mfma_f32_16x16x32_bf16 v[94:97], v[196:199], v[172:175], v[94:97]
	v_mfma_f32_16x16x32_bf16 v[90:93], v[212:215], v[172:175], v[90:93]
	v_mfma_f32_16x16x32_bf16 v[78:81], v[196:199], v[180:183], v[78:81]
	v_mfma_f32_16x16x32_bf16 v[74:77], v[212:215], v[180:183], v[74:77]
	v_mfma_f32_16x16x32_bf16 v[70:73], v[196:199], v[188:191], v[70:73]
	v_mfma_f32_16x16x32_bf16 v[66:69], v[212:215], v[188:191], v[66:69]
	s_mov_b32 m0, s65
	s_add_u32 s100, s58, s22
	s_addc_u32 s101, s59, s23
	s_barrier
	ds_read_b128 v[160:163], v143 offset:16384
	ds_read_b128 v[164:167], v143 offset:17408
	ds_read_b128 v[168:171], v143 offset:18432
	ds_read_b128 v[172:175], v143 offset:19456
	ds_read_b128 v[176:179], v143 offset:20480
	ds_read_b128 v[180:183], v143 offset:21504
	ds_read_b128 v[184:187], v143 offset:22528
	ds_read_b128 v[188:191], v143 offset:23552
	global_load_lds_dwordx4 v134, s[58:59]
	s_mov_b32 m0, s68
	s_nop 0
	global_load_lds_dwordx4 v132, s[58:59]
	s_waitcnt vmcnt(10)
	s_barrier
	s_waitcnt lgkmcnt(0)
	v_mfma_f32_16x16x32_bf16 v[62:65], v[144:147], v[160:163], v[62:65]
	v_mfma_f32_16x16x32_bf16 v[58:61], v[152:155], v[160:163], v[58:61]
	v_mfma_f32_16x16x32_bf16 v[54:57], v[144:147], v[168:171], v[54:57]
	v_mfma_f32_16x16x32_bf16 v[50:53], v[152:155], v[168:171], v[50:53]
	v_mfma_f32_16x16x32_bf16 v[38:41], v[144:147], v[176:179], v[38:41]
	v_mfma_f32_16x16x32_bf16 v[34:37], v[152:155], v[176:179], v[34:37]
	v_mfma_f32_16x16x32_bf16 v[22:25], v[144:147], v[184:187], v[22:25]
	v_mfma_f32_16x16x32_bf16 v[18:21], v[152:155], v[184:187], v[18:21]
	v_mfma_f32_16x16x32_bf16 v[62:65], v[148:151], v[164:167], v[62:65]
	v_mfma_f32_16x16x32_bf16 v[58:61], v[156:159], v[164:167], v[58:61]
	v_mfma_f32_16x16x32_bf16 v[54:57], v[148:151], v[172:175], v[54:57]
	v_mfma_f32_16x16x32_bf16 v[50:53], v[156:159], v[172:175], v[50:53]
	v_mfma_f32_16x16x32_bf16 v[38:41], v[148:151], v[180:183], v[38:41]
	v_mfma_f32_16x16x32_bf16 v[34:37], v[156:159], v[180:183], v[34:37]
	v_mfma_f32_16x16x32_bf16 v[22:25], v[148:151], v[188:191], v[22:25]
	v_mfma_f32_16x16x32_bf16 v[18:21], v[156:159], v[188:191], v[18:21]
	s_barrier
	ds_read_b128 v[144:147], v202 offset:32768
	ds_read_b128 v[148:151], v202 offset:33792
	ds_read_b128 v[152:155], v202 offset:34816
	ds_read_b128 v[156:159], v202 offset:35840
	s_add_u32 s82, s56, 0x80000
	s_addc_u32 s83, s57, 0
	s_add_i32 s81, s84, s64
	s_mov_b32 m0, s81
	s_nop 0
	global_load_lds_dwordx4 v0, s[82:83]
	s_add_i32 m0, s81, 0x2000
	s_nop 0
	global_load_lds_dwordx4 v130, s[82:83]
	s_waitcnt vmcnt(6)
	s_barrier
; #define PG8_STAGE(bufoff, gbase, voff) do { _Pragma("unroll") for (int _i = 0; _i < 2; ++_i) \
;         __builtin_amdgcn_global_load_lds((const unsigned*)((const char*)(gbase) + (voff)[_i]), (LAS unsigned*)(lds + (bufoff) + ldsw + _i * 8192), 16, 0, 0); } while (0)
; #define PG8_LDA(dst, b, h) do { _Pragma("unroll") for (int m = 0; m < 4; ++m) _Pragma("unroll") for (int k = 0; k < 2; ++k) dst[m][k] = *(const LAS bf16x8*)(lds + PG8_SA(b, h) + aoff + m * 2048 + k * 1024); } while (0)
; #define PG8_LDB(dst, b, h) do { _Pragma("unroll") for (int n = 0; n < 2; ++n) _Pragma("unroll") for (int k = 0; k < 2; ++k) dst[n][k] = *(const LAS bf16x8*)(lds + PG8_SB(b, h) + boff + n * 2048 + k * 1024); } while (0)
; #define PG8_MMA(ai, bj, At, Bt) do { __builtin_amdgcn_s_setprio(1); _Pragma("unroll") for (int m = 0; m < 4; ++m) _Pragma("unroll") for (int n = 0; n < 2; ++n) _Pragma("unroll") for (int k = 0; k < 2; ++k) \
;         acc[ai][bj][m][n] = __builtin_amdgcn_mfma_f32_16x16x32_bf16(Bt[n][k], At[m][k], acc[ai][bj][m][n], 0, 0, 0); __builtin_amdgcn_s_setprio(0); } while (0)
; #define PG8_WAIT_V(n) asm volatile("s_waitcnt vmcnt(" #n ")" ::: "memory")
; #define PG8_WAIT_L(n) asm volatile("s_waitcnt lgkmcnt(" #n ")" ::: "memory")
; #define PG8_BAR __builtin_amdgcn_s_barrier()
; #define PG8_SCHED __builtin_amdgcn_sched_barrier(0)
; template <class Epi>
; __device__ __forceinline__ void gemm_phase(LAS unsigned char* lds, const Gemm g, const StaticOrder& S, const Epi& E) {
;     ...
;             PG8_WAIT_V(6); PG8_BAR; PG8_MMA(1, 1, At, B1); PG8_BAR;
;             PG8_LDB(B0, 1, 0); PG8_SCHED; PG8_LDA(At, 1, 0); PG8_STAGE(PG8_SA(0, 1), a2 + hstep, voffA);
;             PG8_WAIT_L(8); PG8_BAR; PG8_WAIT_L(0); PG8_MMA(0, 0, At, B0); PG8_BAR; PG8_SCHED;
;             PG8_LDB(B1, 1, 1); PG8_STAGE(PG8_SB(1, 0), b3, voffB);
;             PG8_BAR; PG8_WAIT_L(0); PG8_MMA(0, 1, At, B1); PG8_BAR;
;             PG8_LDA(At, 1, 1); PG8_STAGE(PG8_SA(1, 0), a3, voffA);
;             PG8_BAR; PG8_WAIT_L(0); PG8_MMA(1, 0, At, B0); PG8_BAR; PG8_SCHED;
;             PG8_STAGE(PG8_SB(1, 1), b3 + hstep, voffB);
;             PG8_WAIT_V(6); PG8_BAR; PG8_MMA(1, 1, At, B1); PG8_BAR;
	v_mfma_f32_16x16x32_bf16 v[46:49], v[192:195], v[160:163], v[46:49]
	v_mfma_f32_16x16x32_bf16 v[42:45], v[208:211], v[160:163], v[42:45]
	v_mfma_f32_16x16x32_bf16 v[30:33], v[192:195], v[168:171], v[30:33]
	v_mfma_f32_16x16x32_bf16 v[26:29], v[208:211], v[168:171], v[26:29]
	v_mfma_f32_16x16x32_bf16 v[14:17], v[192:195], v[176:179], v[14:17]
	v_mfma_f32_16x16x32_bf16 v[10:13], v[208:211], v[176:179], v[10:13]
	v_mfma_f32_16x16x32_bf16 v[6:9], v[192:195], v[184:187], v[6:9]
	v_mfma_f32_16x16x32_bf16 v[2:5], v[208:211], v[184:187], v[2:5]
	v_mfma_f32_16x16x32_bf16 v[46:49], v[196:199], v[164:167], v[46:49]
	v_mfma_f32_16x16x32_bf16 v[42:45], v[212:215], v[164:167], v[42:45]
	v_mfma_f32_16x16x32_bf16 v[30:33], v[196:199], v[172:175], v[30:33]
	v_mfma_f32_16x16x32_bf16 v[26:29], v[212:215], v[172:175], v[26:29]
	v_mfma_f32_16x16x32_bf16 v[14:17], v[196:199], v[180:183], v[14:17]
	v_mfma_f32_16x16x32_bf16 v[10:13], v[212:215], v[180:183], v[10:13]
	v_mfma_f32_16x16x32_bf16 v[6:9], v[196:199], v[188:191], v[6:9]
	v_mfma_f32_16x16x32_bf16 v[2:5], v[212:215], v[188:191], v[2:5]
	s_add_i32 s81, 0, 0x18000
	s_barrier
	s_add_u32 s58, s58, 0x80000
	s_addc_u32 s59, s59, 0
	s_mov_b32 m0, s69
	ds_read_b128 v[160:163], v143 offset:32768
	ds_read_b128 v[164:167], v143 offset:33792
	ds_read_b128 v[168:171], v143 offset:34816
	ds_read_b128 v[172:175], v143 offset:35840
	ds_read_b128 v[176:179], v143 offset:36864
	ds_read_b128 v[180:183], v143 offset:37888
	ds_read_b128 v[184:187], v143 offset:38912
	ds_read_b128 v[188:191], v143 offset:39936
	global_load_lds_dwordx4 v134, s[58:59]
	s_mov_b32 m0, s70
	s_nop 0
	global_load_lds_dwordx4 v132, s[58:59]
	s_waitcnt lgkmcnt(8)
	s_barrier
	s_waitcnt lgkmcnt(0)
	v_mfma_f32_16x16x32_bf16 v[126:129], v[144:147], v[160:163], v[126:129]
	v_mfma_f32_16x16x32_bf16 v[122:125], v[152:155], v[160:163], v[122:125]
	v_mfma_f32_16x16x32_bf16 v[118:121], v[144:147], v[168:171], v[118:121]
	v_mfma_f32_16x16x32_bf16 v[114:117], v[152:155], v[168:171], v[114:117]
	v_mfma_f32_16x16x32_bf16 v[102:105], v[144:147], v[176:179], v[102:105]
	v_mfma_f32_16x16x32_bf16 v[98:101], v[152:155], v[176:179], v[98:101]
	v_mfma_f32_16x16x32_bf16 v[86:89], v[144:147], v[184:187], v[86:89]
	v_mfma_f32_16x16x32_bf16 v[82:85], v[152:155], v[184:187], v[82:85]
	v_mfma_f32_16x16x32_bf16 v[126:129], v[148:151], v[164:167], v[126:129]
	v_mfma_f32_16x16x32_bf16 v[122:125], v[156:159], v[164:167], v[122:125]
	v_mfma_f32_16x16x32_bf16 v[118:121], v[148:151], v[172:175], v[118:121]
	v_mfma_f32_16x16x32_bf16 v[114:117], v[156:159], v[172:175], v[114:117]
	v_mfma_f32_16x16x32_bf16 v[102:105], v[148:151], v[180:183], v[102:105]
	v_mfma_f32_16x16x32_bf16 v[98:101], v[156:159], v[180:183], v[98:101]
	v_mfma_f32_16x16x32_bf16 v[86:89], v[148:151], v[188:191], v[86:89]
	v_mfma_f32_16x16x32_bf16 v[82:85], v[156:159], v[188:191], v[82:85]
	s_barrier
	s_add_i32 s58, 0, 0x1c000
	s_add_i32 s59, s81, s64
	s_mov_b32 m0, s59
	ds_read_b128 v[192:195], v202 offset:49152
	ds_read_b128 v[196:199], v202 offset:50176
	ds_read_b128 v[208:211], v202 offset:51200
	ds_read_b128 v[212:215], v202 offset:52224
	global_load_lds_dwordx4 v0, s[98:99]
	s_add_i32 m0, s59, 0x2000
	s_nop 0
	global_load_lds_dwordx4 v130, s[98:99]
	s_barrier
	s_waitcnt lgkmcnt(0)
	v_mfma_f32_16x16x32_bf16 v[110:113], v[192:195], v[160:163], v[110:113]
	v_mfma_f32_16x16x32_bf16 v[106:109], v[208:211], v[160:163], v[106:109]
	v_mfma_f32_16x16x32_bf16 v[94:97], v[192:195], v[168:171], v[94:97]
	v_mfma_f32_16x16x32_bf16 v[90:93], v[208:211], v[168:171], v[90:93]
	v_mfma_f32_16x16x32_bf16 v[78:81], v[192:195], v[176:179], v[78:81]
	v_mfma_f32_16x16x32_bf16 v[74:77], v[208:211], v[176:179], v[74:77]
	v_mfma_f32_16x16x32_bf16 v[70:73], v[192:195], v[184:187], v[70:73]
	v_mfma_f32_16x16x32_bf16 v[66:69], v[208:211], v[184:187], v[66:69]
	v_mfma_f32_16x16x32_bf16 v[110:113], v[196:199], v[164:167], v[110:113]
	v_mfma_f32_16x16x32_bf16 v[106:109], v[212:215], v[164:167], v[106:109]
	v_mfma_f32_16x16x32_bf16 v[94:97], v[196:199], v[172:175], v[94:97]
	v_mfma_f32_16x16x32_bf16 v[90:93], v[212:215], v[172:175], v[90:93]
	v_mfma_f32_16x16x32_bf16 v[78:81], v[196:199], v[180:183], v[78:81]
	v_mfma_f32_16x16x32_bf16 v[74:77], v[212:215], v[180:183], v[74:77]
	v_mfma_f32_16x16x32_bf16 v[70:73], v[196:199], v[188:191], v[70:73]
	v_mfma_f32_16x16x32_bf16 v[66:69], v[212:215], v[188:191], v[66:69]
	s_mov_b32 m0, s71
	s_barrier
	ds_read_b128 v[160:163], v143 offset:49152
	ds_read_b128 v[164:167], v143 offset:50176
	ds_read_b128 v[168:171], v143 offset:51200
	ds_read_b128 v[172:175], v143 offset:52224
	ds_read_b128 v[176:179], v143 offset:53248
	ds_read_b128 v[180:183], v143 offset:54272
	ds_read_b128 v[184:187], v143 offset:55296
	ds_read_b128 v[188:191], v143 offset:56320
	global_load_lds_dwordx4 v134, s[100:101]
	s_mov_b32 m0, s72
	s_nop 0
	global_load_lds_dwordx4 v132, s[100:101]
	s_waitcnt vmcnt(10)
	s_barrier
	s_waitcnt lgkmcnt(0)
	v_mfma_f32_16x16x32_bf16 v[62:65], v[144:147], v[160:163], v[62:65]
	v_mfma_f32_16x16x32_bf16 v[58:61], v[152:155], v[160:163], v[58:61]
	v_mfma_f32_16x16x32_bf16 v[54:57], v[144:147], v[168:171], v[54:57]
	v_mfma_f32_16x16x32_bf16 v[50:53], v[152:155], v[168:171], v[50:53]
	v_mfma_f32_16x16x32_bf16 v[38:41], v[144:147], v[176:179], v[38:41]
	v_mfma_f32_16x16x32_bf16 v[34:37], v[152:155], v[176:179], v[34:37]
	v_mfma_f32_16x16x32_bf16 v[22:25], v[144:147], v[184:187], v[22:25]
	v_mfma_f32_16x16x32_bf16 v[18:21], v[152:155], v[184:187], v[18:21]
	v_mfma_f32_16x16x32_bf16 v[62:65], v[148:151], v[164:167], v[62:65]
	v_mfma_f32_16x16x32_bf16 v[58:61], v[156:159], v[164:167], v[58:61]
	v_mfma_f32_16x16x32_bf16 v[54:57], v[148:151], v[172:175], v[54:57]
	v_mfma_f32_16x16x32_bf16 v[50:53], v[156:159], v[172:175], v[50:53]
	v_mfma_f32_16x16x32_bf16 v[38:41], v[148:151], v[180:183], v[38:41]
	v_mfma_f32_16x16x32_bf16 v[34:37], v[156:159], v[180:183], v[34:37]
	v_mfma_f32_16x16x32_bf16 v[22:25], v[148:151], v[188:191], v[22:25]
	v_mfma_f32_16x16x32_bf16 v[18:21], v[156:159], v[188:191], v[18:21]
	s_barrier
; __device__ __forceinline__ unsigned pk2(float lo, float hi) { f32x2 v = {lo, hi}; bf16x2_t b = __builtin_convertvector(v, bf16x2_t); return __builtin_bit_cast(unsigned, b); }
; #define PG8_STAGE(bufoff, gbase, voff) do { _Pragma("unroll") for (int _i = 0; _i < 2; ++_i) \
;         __builtin_amdgcn_global_load_lds((const unsigned*)((const char*)(gbase) + (voff)[_i]), (LAS unsigned*)(lds + (bufoff) + ldsw + _i * 8192), 16, 0, 0); } while (0)
; #define PG8_LDA(dst, b, h) do { _Pragma("unroll") for (int m = 0; m < 4; ++m) _Pragma("unroll") for (int k = 0; k < 2; ++k) dst[m][k] = *(const LAS bf16x8*)(lds + PG8_SA(b, h) + aoff + m * 2048 + k * 1024); } while (0)
; #define PG8_LDB(dst, b, h) do { _Pragma("unroll") for (int n = 0; n < 2; ++n) _Pragma("unroll") for (int k = 0; k < 2; ++k) dst[n][k] = *(const LAS bf16x8*)(lds + PG8_SB(b, h) + boff + n * 2048 + k * 1024); } while (0)
; #define PG8_WAIT_V(n) asm volatile("s_waitcnt vmcnt(" #n ")" ::: "memory")
; #define PG8_WAIT_L(n) asm volatile("s_waitcnt lgkmcnt(" #n ")" ::: "memory")
; #define PG8_BAR __builtin_amdgcn_s_barrier()
;     __device__ __forceinline__ void operator()(const AccT& acc, const Unit& u, int wr, int wc, int fr, int fq) const {
;     ...
; #pragma unroll
;         for (int ai = 0; ai < 2; ++ai)
; #pragma unroll
;             for (int m = 0; m < 4; ++m) {
;                 const int row = row0 + ai * HALF + m * 16;
;                 const float rs = rsv[ai * 4 + m];
; #pragma unroll
;                 for (int bj = 0; bj < 2; ++bj) {
;                     const f32x4 v0 = acc[ai][bj][m][0] * rs, v1 = acc[ai][bj][m][1] * rs;
;                     u32x4 w; w.x = pk2(v0[0], v0[1]); w.y = pk2(v0[2], v0[3]); w.z = pk2(v1[0], v1[1]); w.w = pk2(v1[2], v1[3]);
;                     *(u32x4*)(out + (size_t)row * ldo + col0 + bj * HALF) = w;
;                 }
; template <class Epi>
; __device__ __forceinline__ void gemm_phase(LAS unsigned char* lds, const Gemm g, const StaticOrder& S, const Epi& E) {
;     ...
;             PG8_LDB(B1, 1, 1); PG8_STAGE(PG8_SB(1, 0), b3, voffB);
;             PG8_BAR; PG8_WAIT_L(0); PG8_MMA(0, 1, At, B1); PG8_BAR;
;             PG8_LDA(At, 1, 1); PG8_STAGE(PG8_SA(1, 0), a3, voffA);
;             PG8_BAR; PG8_WAIT_L(0); PG8_MMA(1, 0, At, B0); PG8_BAR; PG8_SCHED;
;             PG8_STAGE(PG8_SB(1, 1), b3 + hstep, voffB);
;             PG8_WAIT_V(6); PG8_BAR; PG8_MMA(1, 1, At, B1); PG8_BAR;
	ds_read_b128 v[144:147], v202
	ds_read_b128 v[148:151], v202 offset:1024
	ds_read_b128 v[152:155], v202 offset:2048
	ds_read_b128 v[156:159], v202 offset:3072
	s_add_u32 s56, s56, 0x80080
	s_addc_u32 s57, s57, 0
	s_add_i32 s58, s58, s64
	s_mov_b32 m0, s58
	s_nop 0
	global_load_lds_dwordx4 v0, s[56:57]
	s_add_i32 m0, s58, 0x2000
	s_nop 0
	global_load_lds_dwordx4 v130, s[56:57]
	s_waitcnt vmcnt(6)
	s_barrier
	v_mfma_f32_16x16x32_bf16 v[46:49], v[192:195], v[160:163], v[46:49]
	v_mfma_f32_16x16x32_bf16 v[42:45], v[208:211], v[160:163], v[42:45]
	v_mfma_f32_16x16x32_bf16 v[30:33], v[192:195], v[168:171], v[30:33]
	v_mfma_f32_16x16x32_bf16 v[26:29], v[208:211], v[168:171], v[26:29]
	v_mfma_f32_16x16x32_bf16 v[14:17], v[192:195], v[176:179], v[14:17]
	v_mfma_f32_16x16x32_bf16 v[10:13], v[208:211], v[176:179], v[10:13]
	v_mfma_f32_16x16x32_bf16 v[6:9], v[192:195], v[184:187], v[6:9]
	v_mfma_f32_16x16x32_bf16 v[2:5], v[208:211], v[184:187], v[2:5]
	v_mfma_f32_16x16x32_bf16 v[46:49], v[196:199], v[164:167], v[46:49]
	v_mfma_f32_16x16x32_bf16 v[42:45], v[212:215], v[164:167], v[42:45]
	v_mfma_f32_16x16x32_bf16 v[30:33], v[196:199], v[172:175], v[30:33]
	v_mfma_f32_16x16x32_bf16 v[26:29], v[212:215], v[172:175], v[26:29]
	v_mfma_f32_16x16x32_bf16 v[14:17], v[196:199], v[180:183], v[14:17]
	v_mfma_f32_16x16x32_bf16 v[10:13], v[212:215], v[180:183], v[10:13]
	v_mfma_f32_16x16x32_bf16 v[6:9], v[196:199], v[188:191], v[6:9]
	v_mfma_f32_16x16x32_bf16 v[2:5], v[212:215], v[188:191], v[2:5]
	s_add_i32 s80, s80, 2
	s_add_u32 s54, s54, 0x100
	s_addc_u32 s55, s55, 0
	s_add_u32 s78, s78, 0x100
	s_addc_u32 s79, s79, 0
	s_cmp_gt_u32 s80, 29
	s_barrier
	s_cbranch_scc0 .LBB0_77
	s_waitcnt lgkmcnt(0)
	v_lshl_add_u32 v146, s74, 8, v140
	v_lshl_or_b32 v144, s75, 8, v142
	v_ashrrev_i32_e32 v147, 31, v146
	v_ashrrev_i32_e32 v145, 31, v144
	v_cvt_pk_bf16_f32 v126, v126, v127
	v_cvt_pk_bf16_f32 v127, v128, v129
	v_cvt_pk_bf16_f32 v128, v122, v123
	v_lshlrev_b64 v[122:123], 11, v[146:147]
	v_cvt_pk_bf16_f32 v129, v124, v125
	v_lshl_add_u64 v[122:123], s[42:43], 0, v[122:123]
	v_lshlrev_b64 v[124:125], 1, v[144:145]
	v_lshl_add_u64 v[122:123], v[122:123], 0, v[124:125]
	v_cvt_pk_bf16_f32 v110, v110, v111
	v_cvt_pk_bf16_f32 v111, v112, v113
	v_cvt_pk_bf16_f32 v112, v106, v107
	v_cvt_pk_bf16_f32 v113, v108, v109
	global_store_dwordx4 v[122:123], v[110:113], off offset:256
	v_cvt_pk_bf16_f32 v94, v94, v95
	v_cvt_pk_bf16_f32 v95, v96, v97
	v_or_b32_e32 v110, 16, v146
	v_ashrrev_i32_e32 v111, 31, v110
	v_lshlrev_b64 v[110:111], 11, v[110:111]
	v_lshl_add_u64 v[110:111], s[42:43], 0, v[110:111]
	v_lshl_add_u64 v[110:111], v[110:111], 0, v[124:125]
	v_cvt_pk_bf16_f32 v96, v90, v91
	v_cvt_pk_bf16_f32 v97, v92, v93
	global_store_dwordx4 v[110:111], v[94:97], off offset:256
	s_mov_b32 s47, 0x40000
	v_cvt_pk_bf16_f32 v62, v62, v63
	v_or_b32_e32 v94, 32, v146
	v_ashrrev_i32_e32 v95, 31, v94
	v_cvt_pk_bf16_f32 v63, v64, v65
	v_cvt_pk_bf16_f32 v65, v60, v61
	s_mov_b64 s[54:55], 0x40000
	v_add_co_u32_e32 v60, vcc, s47, v122
	v_lshlrev_b64 v[94:95], 11, v[94:95]
	v_cvt_pk_bf16_f32 v64, v58, v59
	v_lshl_add_u64 v[58:59], v[122:123], 0, s[54:55]
	v_addc_co_u32_e32 v61, vcc, 0, v123, vcc
	v_cvt_pk_bf16_f32 v46, v46, v47
	v_cvt_pk_bf16_f32 v47, v48, v49
	v_cvt_pk_bf16_f32 v48, v42, v43
	v_cvt_pk_bf16_f32 v49, v44, v45
	s_mov_b32 s47, 0x48000
	v_lshl_add_u64 v[94:95], s[42:43], 0, v[94:95]
	global_store_dwordx4 v[58:59], v[46:49], off offset:256
	s_mov_b64 s[54:55], 0x48000
	v_lshl_add_u64 v[94:95], v[94:95], 0, v[124:125]
	v_add_co_u32_e32 v48, vcc, s47, v122
	v_cvt_pk_bf16_f32 v78, v78, v79
	v_cvt_pk_bf16_f32 v79, v80, v81
	v_cvt_pk_bf16_f32 v80, v74, v75
	v_cvt_pk_bf16_f32 v81, v76, v77
	v_lshl_add_u64 v[46:47], v[122:123], 0, s[54:55]
	v_addc_co_u32_e32 v49, vcc, 0, v123, vcc
	v_cvt_pk_bf16_f32 v30, v30, v31
	v_cvt_pk_bf16_f32 v31, v32, v33
	v_cvt_pk_bf16_f32 v32, v26, v27
	v_cvt_pk_bf16_f32 v33, v28, v29
	s_mov_b32 s47, 0x50000
	global_store_dwordx4 v[94:95], v[78:81], off offset:256
	global_store_dwordx4 v[46:47], v[30:33], off offset:256
	s_mov_b64 s[54:55], 0x50000
	v_or_b32_e32 v78, 48, v146
	v_add_co_u32_e32 v32, vcc, s47, v122
	v_ashrrev_i32_e32 v79, 31, v78
	v_lshl_add_u64 v[30:31], v[122:123], 0, s[54:55]
	v_addc_co_u32_e32 v33, vcc, 0, v123, vcc
	v_cvt_pk_bf16_f32 v14, v14, v15
	v_cvt_pk_bf16_f32 v15, v16, v17
	v_cvt_pk_bf16_f32 v16, v10, v11
	v_cvt_pk_bf16_f32 v17, v12, v13
	s_mov_b32 s47, 0x58000
	v_lshlrev_b64 v[78:79], 11, v[78:79]
	global_store_dwordx4 v[30:31], v[14:17], off offset:256
	v_lshl_add_u64 v[78:79], s[42:43], 0, v[78:79]
	s_mov_b64 s[54:55], 0x58000
	v_add_co_u32_e32 v16, vcc, s47, v122
	v_cvt_pk_bf16_f32 v106, v118, v119
	s_nop 0
	v_addc_co_u32_e32 v17, vcc, 0, v123, vcc
	v_cvt_pk_bf16_f32 v107, v120, v121
	v_cvt_pk_bf16_f32 v108, v114, v115
	v_cvt_pk_bf16_f32 v109, v116, v117
	v_cvt_pk_bf16_f32 v90, v102, v103
	v_cvt_pk_bf16_f32 v91, v104, v105
	v_cvt_pk_bf16_f32 v92, v98, v99
	v_cvt_pk_bf16_f32 v93, v100, v101
	v_cvt_pk_bf16_f32 v74, v86, v87
	v_cvt_pk_bf16_f32 v75, v88, v89
	v_cvt_pk_bf16_f32 v76, v82, v83
	v_cvt_pk_bf16_f32 v77, v84, v85
	v_lshl_add_u64 v[78:79], v[78:79], 0, v[124:125]
	v_cvt_pk_bf16_f32 v70, v70, v71
	v_cvt_pk_bf16_f32 v71, v72, v73
	v_cvt_pk_bf16_f32 v72, v66, v67
	v_cvt_pk_bf16_f32 v73, v68, v69
	v_cvt_pk_bf16_f32 v42, v54, v55
	v_cvt_pk_bf16_f32 v43, v56, v57
	v_cvt_pk_bf16_f32 v44, v50, v51
	v_cvt_pk_bf16_f32 v45, v52, v53
	v_cvt_pk_bf16_f32 v26, v38, v39
	v_cvt_pk_bf16_f32 v27, v40, v41
	v_cvt_pk_bf16_f32 v28, v34, v35
	v_cvt_pk_bf16_f32 v29, v36, v37
	v_cvt_pk_bf16_f32 v10, v22, v23
	v_cvt_pk_bf16_f32 v11, v24, v25
	v_cvt_pk_bf16_f32 v12, v18, v19
	v_cvt_pk_bf16_f32 v13, v20, v21
	v_lshl_add_u64 v[14:15], v[122:123], 0, s[54:55]
	v_cvt_pk_bf16_f32 v6, v6, v7
	v_cvt_pk_bf16_f32 v7, v8, v9
	v_cvt_pk_bf16_f32 v8, v2, v3
	v_cvt_pk_bf16_f32 v9, v4, v5
	s_and_b64 vcc, exec, s[44:45]
	s_mov_b32 s75, s46
	s_mov_b32 s74, s48
	s_mov_b64 s[56:57], s[52:53]
	s_mov_b64 s[54:55], s[50:51]
	global_store_dwordx4 v[122:123], v[126:129], off
	global_store_dwordx4 v[110:111], v[106:109], off
	global_store_dwordx4 v[94:95], v[90:93], off
	global_store_dwordx4 v[78:79], v[74:77], off
	global_store_dwordx4 v[78:79], v[70:73], off offset:256
	global_store_dwordx4 v[60:61], v[62:65], off
	global_store_dwordx4 v[48:49], v[42:45], off
	global_store_dwordx4 v[32:33], v[26:29], off
	global_store_dwordx4 v[16:17], v[10:13], off
	global_store_dwordx4 v[14:15], v[6:9], off offset:256
	s_cbranch_vccz .LBB0_74
	s_waitcnt vmcnt(0)
	s_cmpk_gt_u32 s60, 0xff
	s_cbranch_scc1 .LBB0_81
	s_barrier

; #define PG8_STAGE(bufoff, gbase, voff) do { _Pragma("unroll") for (int _i = 0; _i < 2; ++_i) \
;         __builtin_amdgcn_global_load_lds((const unsigned*)((const char*)(gbase) + (voff)[_i]), (LAS unsigned*)(lds + (bufoff) + ldsw + _i * 8192), 16, 0, 0); } while (0)
; #define PG8_LDA(dst, b, h) do { _Pragma("unroll") for (int m = 0; m < 4; ++m) _Pragma("unroll") for (int k = 0; k < 2; ++k) dst[m][k] = *(const LAS bf16x8*)(lds + PG8_SA(b, h) + aoff + m * 2048 + k * 1024); } while (0)
; #define PG8_LDB(dst, b, h) do { _Pragma("unroll") for (int n = 0; n < 2; ++n) _Pragma("unroll") for (int k = 0; k < 2; ++k) dst[n][k] = *(const LAS bf16x8*)(lds + PG8_SB(b, h) + boff + n * 2048 + k * 1024); } while (0)
; #define PG8_MMA(ai, bj, At, Bt) do { __builtin_amdgcn_s_setprio(1); _Pragma("unroll") for (int m = 0; m < 4; ++m) _Pragma("unroll") for (int n = 0; n < 2; ++n) _Pragma("unroll") for (int k = 0; k < 2; ++k) \
;         acc[ai][bj][m][n] = __builtin_amdgcn_mfma_f32_16x16x32_bf16(Bt[n][k], At[m][k], acc[ai][bj][m][n], 0, 0, 0); __builtin_amdgcn_s_setprio(0); } while (0)
; #define PG8_WAIT_V(n) asm volatile("s_waitcnt vmcnt(" #n ")" ::: "memory")
; #define PG8_WAIT_L(n) asm volatile("s_waitcnt lgkmcnt(" #n ")" ::: "memory")
; template <class Epi>
; __device__ __forceinline__ void gemm_phase(LAS unsigned char* lds, const Gemm g, const StaticOrder& S, const Epi& E) {
;     ...
;         for (int t = 0; t < nt; t += 2) {
;             const bool last = (t == nt - 2);
;             const char* a1 = cA + (size_t)(t + 1) * kstep;
;             const char* a2 = last ? nA : cA + (size_t)(t + 2) * kstep; const char* b2 = last ? nB : cB + (size_t)(t + 2) * kstep;
;             const char* a3 = a2 + kstep; const char* b3 = b2 + kstep;
;             PG8_LDB(B0, 0, 0); PG8_SCHED; PG8_LDA(At, 0, 0); PG8_STAGE(PG8_SA(1, 1), a1 + hstep, voffA);
;             PG8_WAIT_L(8); PG8_BAR; PG8_WAIT_L(0); PG8_MMA(0, 0, At, B0); PG8_BAR; PG8_SCHED;
;             PG8_LDB(B1, 0, 1); PG8_STAGE(PG8_SB(0, 0), b2, voffB);
;             PG8_BAR; PG8_WAIT_L(0); PG8_MMA(0, 1, At, B1); PG8_BAR;
;             PG8_LDA(At, 0, 1); PG8_STAGE(PG8_SA(0, 0), a2, voffA);
;             PG8_BAR; PG8_WAIT_L(0); PG8_MMA(1, 0, At, B0); PG8_BAR; PG8_SCHED;
;             PG8_STAGE(PG8_SB(0, 1), b2 + hstep, voffB);
;             PG8_WAIT_V(6); PG8_BAR; PG8_MMA(1, 1, At, B1); PG8_BAR;
.LBB0_90:
	s_add_u32 s48, s46, 0xfff80080
	s_addc_u32 s49, s47, -1
	s_add_i32 s74, 0, 0x10000
	s_cmp_eq_u32 s73, 28
	s_cselect_b32 s51, s41, s49
	s_cselect_b32 s50, s69, s48
	s_cselect_b32 s49, s39, s72
	s_cselect_b32 s48, s70, s71
	s_add_i32 m0, s56, 0xc000
	ds_read_b128 v[168:171], v151
	ds_read_b128 v[172:175], v151 offset:1024
	ds_read_b128 v[176:179], v151 offset:2048
	ds_read_b128 v[180:183], v151 offset:3072
	ds_read_b128 v[184:187], v151 offset:4096
	ds_read_b128 v[188:191], v151 offset:5120
	ds_read_b128 v[192:195], v151 offset:6144
	ds_read_b128 v[196:199], v151 offset:7168
	global_load_lds_dwordx4 v136, s[46:47]
	s_add_i32 m0, s56, 0xe000
	s_nop 0
	global_load_lds_dwordx4 v138, s[46:47]
	s_waitcnt lgkmcnt(8)
	s_barrier
	s_waitcnt lgkmcnt(0)
	v_mfma_f32_16x16x32_bf16 v[126:129], v[152:155], v[168:171], v[126:129]
	v_mfma_f32_16x16x32_bf16 v[122:125], v[160:163], v[168:171], v[122:125]
	v_mfma_f32_16x16x32_bf16 v[110:113], v[152:155], v[176:179], v[110:113]
	v_mfma_f32_16x16x32_bf16 v[102:105], v[160:163], v[176:179], v[102:105]
	v_mfma_f32_16x16x32_bf16 v[94:97], v[152:155], v[184:187], v[94:97]
	v_mfma_f32_16x16x32_bf16 v[86:89], v[160:163], v[184:187], v[86:89]
	v_mfma_f32_16x16x32_bf16 v[78:81], v[152:155], v[192:195], v[78:81]
	v_mfma_f32_16x16x32_bf16 v[70:73], v[160:163], v[192:195], v[70:73]
	v_mfma_f32_16x16x32_bf16 v[126:129], v[156:159], v[172:175], v[126:129]
	v_mfma_f32_16x16x32_bf16 v[122:125], v[164:167], v[172:175], v[122:125]
	v_mfma_f32_16x16x32_bf16 v[110:113], v[156:159], v[180:183], v[110:113]
	v_mfma_f32_16x16x32_bf16 v[102:105], v[164:167], v[180:183], v[102:105]
	v_mfma_f32_16x16x32_bf16 v[94:97], v[156:159], v[188:191], v[94:97]
	v_mfma_f32_16x16x32_bf16 v[86:89], v[164:167], v[188:191], v[86:89]
	v_mfma_f32_16x16x32_bf16 v[78:81], v[156:159], v[196:199], v[78:81]
	v_mfma_f32_16x16x32_bf16 v[70:73], v[164:167], v[196:199], v[70:73]
	s_barrier
	s_add_i32 s76, 0, 0x14000
	s_add_i32 s74, s74, s55
	s_mov_b32 m0, s74
	ds_read_b128 v[208:211], v200 offset:16384
	ds_read_b128 v[212:215], v200 offset:17408
	ds_read_b128 v[216:219], v200 offset:18432
	ds_read_b128 v[220:223], v200 offset:19456
	global_load_lds_dwordx4 v0, s[48:49]
	s_add_i32 m0, s74, 0x2000
	s_add_u32 s98, s48, s22
	global_load_lds_dwordx4 v130, s[48:49]
	s_addc_u32 s99, s49, s23
	s_barrier
	s_waitcnt lgkmcnt(0)
	v_mfma_f32_16x16x32_bf16 v[118:121], v[208:211], v[168:171], v[118:121]
	v_mfma_f32_16x16x32_bf16 v[114:117], v[216:219], v[168:171], v[114:117]
	v_mfma_f32_16x16x32_bf16 v[106:109], v[208:211], v[176:179], v[106:109]
	v_mfma_f32_16x16x32_bf16 v[98:101], v[216:219], v[176:179], v[98:101]
	v_mfma_f32_16x16x32_bf16 v[90:93], v[208:211], v[184:187], v[90:93]
	v_mfma_f32_16x16x32_bf16 v[82:85], v[216:219], v[184:187], v[82:85]
	v_mfma_f32_16x16x32_bf16 v[74:77], v[208:211], v[192:195], v[74:77]
	v_mfma_f32_16x16x32_bf16 v[66:69], v[216:219], v[192:195], v[66:69]
	v_mfma_f32_16x16x32_bf16 v[118:121], v[212:215], v[172:175], v[118:121]
	v_mfma_f32_16x16x32_bf16 v[114:117], v[220:223], v[172:175], v[114:117]
	v_mfma_f32_16x16x32_bf16 v[106:109], v[212:215], v[180:183], v[106:109]
	v_mfma_f32_16x16x32_bf16 v[98:101], v[220:223], v[180:183], v[98:101]
	v_mfma_f32_16x16x32_bf16 v[90:93], v[212:215], v[188:191], v[90:93]
	v_mfma_f32_16x16x32_bf16 v[82:85], v[220:223], v[188:191], v[82:85]
	v_mfma_f32_16x16x32_bf16 v[74:77], v[212:215], v[196:199], v[74:77]
	v_mfma_f32_16x16x32_bf16 v[66:69], v[220:223], v[196:199], v[66:69]
	s_mov_b32 m0, s56
	s_add_u32 s100, s50, s22
	s_addc_u32 s101, s51, s23
	s_barrier
	ds_read_b128 v[168:171], v151 offset:16384
	ds_read_b128 v[172:175], v151 offset:17408
	ds_read_b128 v[176:179], v151 offset:18432
	ds_read_b128 v[180:183], v151 offset:19456
	ds_read_b128 v[184:187], v151 offset:20480
	ds_read_b128 v[188:191], v151 offset:21504
	ds_read_b128 v[192:195], v151 offset:22528
	ds_read_b128 v[196:199], v151 offset:23552
	global_load_lds_dwordx4 v134, s[50:51]
	s_mov_b32 m0, s57
	s_nop 0
	global_load_lds_dwordx4 v132, s[50:51]
	s_waitcnt vmcnt(10)
	s_barrier
	s_waitcnt lgkmcnt(0)
	v_mfma_f32_16x16x32_bf16 v[62:65], v[152:155], v[168:171], v[62:65]
	v_mfma_f32_16x16x32_bf16 v[54:57], v[160:163], v[168:171], v[54:57]
	v_mfma_f32_16x16x32_bf16 v[46:49], v[152:155], v[176:179], v[46:49]
	v_mfma_f32_16x16x32_bf16 v[38:41], v[160:163], v[176:179], v[38:41]
	v_mfma_f32_16x16x32_bf16 v[30:33], v[152:155], v[184:187], v[30:33]
	v_mfma_f32_16x16x32_bf16 v[22:25], v[160:163], v[184:187], v[22:25]
	v_mfma_f32_16x16x32_bf16 v[14:17], v[152:155], v[192:195], v[14:17]
	v_mfma_f32_16x16x32_bf16 v[6:9], v[160:163], v[192:195], v[6:9]
	v_mfma_f32_16x16x32_bf16 v[62:65], v[156:159], v[172:175], v[62:65]
	v_mfma_f32_16x16x32_bf16 v[54:57], v[164:167], v[172:175], v[54:57]
	v_mfma_f32_16x16x32_bf16 v[46:49], v[156:159], v[180:183], v[46:49]
	v_mfma_f32_16x16x32_bf16 v[38:41], v[164:167], v[180:183], v[38:41]
	v_mfma_f32_16x16x32_bf16 v[30:33], v[156:159], v[188:191], v[30:33]
	v_mfma_f32_16x16x32_bf16 v[22:25], v[164:167], v[188:191], v[22:25]
	v_mfma_f32_16x16x32_bf16 v[14:17], v[156:159], v[196:199], v[14:17]
	v_mfma_f32_16x16x32_bf16 v[6:9], v[164:167], v[196:199], v[6:9]
	s_barrier
	ds_read_b128 v[152:155], v200 offset:32768
	ds_read_b128 v[156:159], v200 offset:33792
	ds_read_b128 v[160:163], v200 offset:34816
	ds_read_b128 v[164:167], v200 offset:35840
	s_add_u32 s74, s48, 0x80000
	s_addc_u32 s75, s49, 0
	s_add_i32 s76, s76, s55
	s_mov_b32 m0, s76
	s_nop 0
	global_load_lds_dwordx4 v0, s[74:75]
	s_add_i32 m0, s76, 0x2000
	s_nop 0
	global_load_lds_dwordx4 v130, s[74:75]
	s_waitcnt vmcnt(6)
	s_barrier
; #define PG8_STAGE(bufoff, gbase, voff) do { _Pragma("unroll") for (int _i = 0; _i < 2; ++_i) \
;         __builtin_amdgcn_global_load_lds((const unsigned*)((const char*)(gbase) + (voff)[_i]), (LAS unsigned*)(lds + (bufoff) + ldsw + _i * 8192), 16, 0, 0); } while (0)
; #define PG8_LDA(dst, b, h) do { _Pragma("unroll") for (int m = 0; m < 4; ++m) _Pragma("unroll") for (int k = 0; k < 2; ++k) dst[m][k] = *(const LAS bf16x8*)(lds + PG8_SA(b, h) + aoff + m * 2048 + k * 1024); } while (0)
; #define PG8_LDB(dst, b, h) do { _Pragma("unroll") for (int n = 0; n < 2; ++n) _Pragma("unroll") for (int k = 0; k < 2; ++k) dst[n][k] = *(const LAS bf16x8*)(lds + PG8_SB(b, h) + boff + n * 2048 + k * 1024); } while (0)
; #define PG8_MMA(ai, bj, At, Bt) do { __builtin_amdgcn_s_setprio(1); _Pragma("unroll") for (int m = 0; m < 4; ++m) _Pragma("unroll") for (int n = 0; n < 2; ++n) _Pragma("unroll") for (int k = 0; k < 2; ++k) \
;         acc[ai][bj][m][n] = __builtin_amdgcn_mfma_f32_16x16x32_bf16(Bt[n][k], At[m][k], acc[ai][bj][m][n], 0, 0, 0); __builtin_amdgcn_s_setprio(0); } while (0)
; #define PG8_WAIT_V(n) asm volatile("s_waitcnt vmcnt(" #n ")" ::: "memory")
; #define PG8_WAIT_L(n) asm volatile("s_waitcnt lgkmcnt(" #n ")" ::: "memory")
; #define PG8_BAR __builtin_amdgcn_s_barrier()
; #define PG8_SCHED __builtin_amdgcn_sched_barrier(0)
; template <class Epi>
; __device__ __forceinline__ void gemm_phase(LAS unsigned char* lds, const Gemm g, const StaticOrder& S, const Epi& E) {
;     ...
;             PG8_WAIT_V(6); PG8_BAR; PG8_MMA(1, 1, At, B1); PG8_BAR;
;             PG8_LDB(B0, 1, 0); PG8_SCHED; PG8_LDA(At, 1, 0); PG8_STAGE(PG8_SA(0, 1), a2 + hstep, voffA);
;             PG8_WAIT_L(8); PG8_BAR; PG8_WAIT_L(0); PG8_MMA(0, 0, At, B0); PG8_BAR; PG8_SCHED;
;             PG8_LDB(B1, 1, 1); PG8_STAGE(PG8_SB(1, 0), b3, voffB);
;             PG8_BAR; PG8_WAIT_L(0); PG8_MMA(0, 1, At, B1); PG8_BAR;
;             PG8_LDA(At, 1, 1); PG8_STAGE(PG8_SA(1, 0), a3, voffA);
;             PG8_BAR; PG8_WAIT_L(0); PG8_MMA(1, 0, At, B0); PG8_BAR; PG8_SCHED;
	v_mfma_f32_16x16x32_bf16 v[58:61], v[208:211], v[168:171], v[58:61]
	v_mfma_f32_16x16x32_bf16 v[50:53], v[216:219], v[168:171], v[50:53]
	v_mfma_f32_16x16x32_bf16 v[42:45], v[208:211], v[176:179], v[42:45]
	v_mfma_f32_16x16x32_bf16 v[34:37], v[216:219], v[176:179], v[34:37]
	v_mfma_f32_16x16x32_bf16 v[26:29], v[208:211], v[184:187], v[26:29]
	v_mfma_f32_16x16x32_bf16 v[18:21], v[216:219], v[184:187], v[18:21]
	v_mfma_f32_16x16x32_bf16 v[10:13], v[208:211], v[192:195], v[10:13]
	v_mfma_f32_16x16x32_bf16 v[2:5], v[216:219], v[192:195], v[2:5]
	v_mfma_f32_16x16x32_bf16 v[58:61], v[212:215], v[172:175], v[58:61]
	v_mfma_f32_16x16x32_bf16 v[50:53], v[220:223], v[172:175], v[50:53]
	v_mfma_f32_16x16x32_bf16 v[42:45], v[212:215], v[180:183], v[42:45]
	v_mfma_f32_16x16x32_bf16 v[34:37], v[220:223], v[180:183], v[34:37]
	v_mfma_f32_16x16x32_bf16 v[26:29], v[212:215], v[188:191], v[26:29]
	v_mfma_f32_16x16x32_bf16 v[18:21], v[220:223], v[188:191], v[18:21]
	v_mfma_f32_16x16x32_bf16 v[10:13], v[212:215], v[196:199], v[10:13]
	v_mfma_f32_16x16x32_bf16 v[2:5], v[220:223], v[196:199], v[2:5]
	s_add_i32 s74, 0, 0x18000
	s_barrier
	s_add_u32 s50, s50, 0x80000
	s_addc_u32 s51, s51, 0
	s_mov_b32 m0, s58
	ds_read_b128 v[168:171], v151 offset:32768
	ds_read_b128 v[172:175], v151 offset:33792
	ds_read_b128 v[176:179], v151 offset:34816
	ds_read_b128 v[180:183], v151 offset:35840
	ds_read_b128 v[184:187], v151 offset:36864
	ds_read_b128 v[188:191], v151 offset:37888
	ds_read_b128 v[192:195], v151 offset:38912
	ds_read_b128 v[196:199], v151 offset:39936
	global_load_lds_dwordx4 v134, s[50:51]
	s_mov_b32 m0, s59
	s_nop 0
	global_load_lds_dwordx4 v132, s[50:51]
	s_waitcnt lgkmcnt(8)
	s_barrier
	s_waitcnt lgkmcnt(0)
	v_mfma_f32_16x16x32_bf16 v[126:129], v[152:155], v[168:171], v[126:129]
	v_mfma_f32_16x16x32_bf16 v[122:125], v[160:163], v[168:171], v[122:125]
	v_mfma_f32_16x16x32_bf16 v[110:113], v[152:155], v[176:179], v[110:113]
	v_mfma_f32_16x16x32_bf16 v[102:105], v[160:163], v[176:179], v[102:105]
	v_mfma_f32_16x16x32_bf16 v[94:97], v[152:155], v[184:187], v[94:97]
	v_mfma_f32_16x16x32_bf16 v[86:89], v[160:163], v[184:187], v[86:89]
	v_mfma_f32_16x16x32_bf16 v[78:81], v[152:155], v[192:195], v[78:81]
	v_mfma_f32_16x16x32_bf16 v[70:73], v[160:163], v[192:195], v[70:73]
	v_mfma_f32_16x16x32_bf16 v[126:129], v[156:159], v[172:175], v[126:129]
	v_mfma_f32_16x16x32_bf16 v[122:125], v[164:167], v[172:175], v[122:125]
	v_mfma_f32_16x16x32_bf16 v[110:113], v[156:159], v[180:183], v[110:113]
	v_mfma_f32_16x16x32_bf16 v[102:105], v[164:167], v[180:183], v[102:105]
	v_mfma_f32_16x16x32_bf16 v[94:97], v[156:159], v[188:191], v[94:97]
	v_mfma_f32_16x16x32_bf16 v[86:89], v[164:167], v[188:191], v[86:89]
	v_mfma_f32_16x16x32_bf16 v[78:81], v[156:159], v[196:199], v[78:81]
	v_mfma_f32_16x16x32_bf16 v[70:73], v[164:167], v[196:199], v[70:73]
	s_barrier
	s_add_i32 s50, 0, 0x1c000
	s_add_i32 s51, s74, s55
	s_mov_b32 m0, s51
	ds_read_b128 v[208:211], v200 offset:49152
	ds_read_b128 v[212:215], v200 offset:50176
	ds_read_b128 v[216:219], v200 offset:51200
	ds_read_b128 v[220:223], v200 offset:52224
	global_load_lds_dwordx4 v0, s[98:99]
	s_add_i32 m0, s51, 0x2000
	s_nop 0
	global_load_lds_dwordx4 v130, s[98:99]
	s_barrier
	s_waitcnt lgkmcnt(0)
	v_mfma_f32_16x16x32_bf16 v[118:121], v[208:211], v[168:171], v[118:121]
	v_mfma_f32_16x16x32_bf16 v[114:117], v[216:219], v[168:171], v[114:117]
	v_mfma_f32_16x16x32_bf16 v[106:109], v[208:211], v[176:179], v[106:109]
	v_mfma_f32_16x16x32_bf16 v[98:101], v[216:219], v[176:179], v[98:101]
	v_mfma_f32_16x16x32_bf16 v[90:93], v[208:211], v[184:187], v[90:93]
	v_mfma_f32_16x16x32_bf16 v[82:85], v[216:219], v[184:187], v[82:85]
	v_mfma_f32_16x16x32_bf16 v[74:77], v[208:211], v[192:195], v[74:77]
	v_mfma_f32_16x16x32_bf16 v[66:69], v[216:219], v[192:195], v[66:69]
	v_mfma_f32_16x16x32_bf16 v[118:121], v[212:215], v[172:175], v[118:121]
	v_mfma_f32_16x16x32_bf16 v[114:117], v[220:223], v[172:175], v[114:117]
	v_mfma_f32_16x16x32_bf16 v[106:109], v[212:215], v[180:183], v[106:109]
	v_mfma_f32_16x16x32_bf16 v[98:101], v[220:223], v[180:183], v[98:101]
	v_mfma_f32_16x16x32_bf16 v[90:93], v[212:215], v[188:191], v[90:93]
	v_mfma_f32_16x16x32_bf16 v[82:85], v[220:223], v[188:191], v[82:85]
	v_mfma_f32_16x16x32_bf16 v[74:77], v[212:215], v[196:199], v[74:77]
	v_mfma_f32_16x16x32_bf16 v[66:69], v[220:223], v[196:199], v[66:69]
	s_mov_b32 m0, s61
	s_barrier
	ds_read_b128 v[168:171], v151 offset:49152
	ds_read_b128 v[172:175], v151 offset:50176
	ds_read_b128 v[176:179], v151 offset:51200
	ds_read_b128 v[180:183], v151 offset:52224
	ds_read_b128 v[184:187], v151 offset:53248
	ds_read_b128 v[188:191], v151 offset:54272
	ds_read_b128 v[192:195], v151 offset:55296
	ds_read_b128 v[196:199], v151 offset:56320
	global_load_lds_dwordx4 v134, s[100:101]
	s_mov_b32 m0, s63
	s_nop 0
	global_load_lds_dwordx4 v132, s[100:101]
	s_waitcnt vmcnt(10)
	s_barrier
	s_waitcnt lgkmcnt(0)
	v_mfma_f32_16x16x32_bf16 v[62:65], v[152:155], v[168:171], v[62:65]
	v_mfma_f32_16x16x32_bf16 v[54:57], v[160:163], v[168:171], v[54:57]
	v_mfma_f32_16x16x32_bf16 v[46:49], v[152:155], v[176:179], v[46:49]
	v_mfma_f32_16x16x32_bf16 v[38:41], v[160:163], v[176:179], v[38:41]
	v_mfma_f32_16x16x32_bf16 v[30:33], v[152:155], v[184:187], v[30:33]
	v_mfma_f32_16x16x32_bf16 v[22:25], v[160:163], v[184:187], v[22:25]
	v_mfma_f32_16x16x32_bf16 v[14:17], v[152:155], v[192:195], v[14:17]
	v_mfma_f32_16x16x32_bf16 v[6:9], v[160:163], v[192:195], v[6:9]
	v_mfma_f32_16x16x32_bf16 v[62:65], v[156:159], v[172:175], v[62:65]
	v_mfma_f32_16x16x32_bf16 v[54:57], v[164:167], v[172:175], v[54:57]
	v_mfma_f32_16x16x32_bf16 v[46:49], v[156:159], v[180:183], v[46:49]
	v_mfma_f32_16x16x32_bf16 v[38:41], v[164:167], v[180:183], v[38:41]
	v_mfma_f32_16x16x32_bf16 v[30:33], v[156:159], v[188:191], v[30:33]
	v_mfma_f32_16x16x32_bf16 v[22:25], v[164:167], v[188:191], v[22:25]
	v_mfma_f32_16x16x32_bf16 v[14:17], v[156:159], v[196:199], v[14:17]
	v_mfma_f32_16x16x32_bf16 v[6:9], v[164:167], v[196:199], v[6:9]
	s_barrier
; #define PG8_STAGE(bufoff, gbase, voff) do { _Pragma("unroll") for (int _i = 0; _i < 2; ++_i) \
;         __builtin_amdgcn_global_load_lds((const unsigned*)((const char*)(gbase) + (voff)[_i]), (LAS unsigned*)(lds + (bufoff) + ldsw + _i * 8192), 16, 0, 0); } while (0)
; #define PG8_MMA(ai, bj, At, Bt) do { __builtin_amdgcn_s_setprio(1); _Pragma("unroll") for (int m = 0; m < 4; ++m) _Pragma("unroll") for (int n = 0; n < 2; ++n) _Pragma("unroll") for (int k = 0; k < 2; ++k) \
;         acc[ai][bj][m][n] = __builtin_amdgcn_mfma_f32_16x16x32_bf16(Bt[n][k], At[m][k], acc[ai][bj][m][n], 0, 0, 0); __builtin_amdgcn_s_setprio(0); } while (0)
; #define PG8_WAIT_V(n) asm volatile("s_waitcnt vmcnt(" #n ")" ::: "memory")
; #define PG8_WAIT_L(n) asm volatile("s_waitcnt lgkmcnt(" #n ")" ::: "memory")
; #define PG8_BAR __builtin_amdgcn_s_barrier()
; #define PG8_SCHED __builtin_amdgcn_sched_barrier(0)
;     __device__ __forceinline__ void operator()(const AccT& acc, const Unit& u, int wr, int wc, int fr, int fq) const {
;     ...
;         {
;             const int ln = (fq << 4) | fr;
;             float sa = ss[u.pm * BM + wr * 64 + ln], sb = ss[u.pm * BM + HALF + wr * 64 + ln];
;             sa = __builtin_amdgcn_rsqf(sa * (1.0f / DM) + EPS); sb = __builtin_amdgcn_rsqf(sb * (1.0f / DM) + EPS);
; #pragma unroll
;             for (int m = 0; m < 4; ++m) { rsv[m] = __shfl(sa, 16 * m + fr); rsv[4 + m] = __shfl(sb, 16 * m + fr); }
;         }
; #pragma unroll
;         for (int ai = 0; ai < 2; ++ai)
; #pragma unroll
;             for (int m = 0; m < 4; ++m) {
;                 const int row = row0 + ai * HALF + m * 16;
;                 const float rs = rsv[ai * 4 + m];
;                 float v[8];
; #pragma unroll
;                 for (int n = 0; n < 2; ++n)
; #pragma unroll
;                     for (int j = 0; j < 4; ++j) {
;                         const float g = acc[ai][0][m][n][j] * rs, up = acc[ai][1][m][n][j] * rs;
;                         const float sg = __builtin_amdgcn_rcpf(1.0f + __builtin_amdgcn_exp2f(-g * LOG2E));
; template <class Epi>
; __device__ __forceinline__ void gemm_phase(LAS unsigned char* lds, const Gemm g, const StaticOrder& S, const Epi& E) {
;     ...
;             PG8_BAR; PG8_WAIT_L(0); PG8_MMA(1, 0, At, B0); PG8_BAR; PG8_SCHED;
;             PG8_STAGE(PG8_SB(1, 1), b3 + hstep, voffB);
;             PG8_WAIT_V(6); PG8_BAR; PG8_MMA(1, 1, At, B1); PG8_BAR;
	ds_read_b128 v[152:155], v200
	ds_read_b128 v[156:159], v200 offset:1024
	ds_read_b128 v[160:163], v200 offset:2048
	ds_read_b128 v[164:167], v200 offset:3072
	s_add_u32 s48, s48, 0x80080
	s_addc_u32 s49, s49, 0
	s_add_i32 s50, s50, s55
	s_mov_b32 m0, s50
	s_nop 0
	global_load_lds_dwordx4 v0, s[48:49]
	s_add_i32 m0, s50, 0x2000
	s_nop 0
	global_load_lds_dwordx4 v130, s[48:49]
	s_waitcnt vmcnt(6)
	s_barrier
	v_mfma_f32_16x16x32_bf16 v[58:61], v[208:211], v[168:171], v[58:61]
	v_mfma_f32_16x16x32_bf16 v[50:53], v[216:219], v[168:171], v[50:53]
	v_mfma_f32_16x16x32_bf16 v[42:45], v[208:211], v[176:179], v[42:45]
	v_mfma_f32_16x16x32_bf16 v[34:37], v[216:219], v[176:179], v[34:37]
	v_mfma_f32_16x16x32_bf16 v[26:29], v[208:211], v[184:187], v[26:29]
	v_mfma_f32_16x16x32_bf16 v[18:21], v[216:219], v[184:187], v[18:21]
	v_mfma_f32_16x16x32_bf16 v[10:13], v[208:211], v[192:195], v[10:13]
	v_mfma_f32_16x16x32_bf16 v[2:5], v[216:219], v[192:195], v[2:5]
	v_mfma_f32_16x16x32_bf16 v[58:61], v[212:215], v[172:175], v[58:61]
	v_mfma_f32_16x16x32_bf16 v[50:53], v[220:223], v[172:175], v[50:53]
	v_mfma_f32_16x16x32_bf16 v[42:45], v[212:215], v[180:183], v[42:45]
	v_mfma_f32_16x16x32_bf16 v[34:37], v[220:223], v[180:183], v[34:37]
	v_mfma_f32_16x16x32_bf16 v[26:29], v[212:215], v[188:191], v[26:29]
	v_mfma_f32_16x16x32_bf16 v[18:21], v[220:223], v[188:191], v[18:21]
	v_mfma_f32_16x16x32_bf16 v[10:13], v[212:215], v[196:199], v[10:13]
	v_mfma_f32_16x16x32_bf16 v[2:5], v[220:223], v[196:199], v[2:5]
	s_add_i32 s73, s73, 2
	s_add_u32 s46, s46, 0x100
	s_addc_u32 s47, s47, 0
	s_add_u32 s71, s71, 0x100
	s_addc_u32 s72, s72, 0
	s_cmp_gt_u32 s73, 29
	s_barrier
	s_cbranch_scc0 .LBB0_90
	s_waitcnt lgkmcnt(0)
	s_lshl_b32 s39, s68, 8
	s_add_i32 s39, s39, s60
	v_or_b32_e32 v154, s39, v145
	v_ashrrev_i32_e32 v155, 31, v154
	v_lshl_add_u64 v[154:155], v[154:155], 2, s[2:3]
	global_load_dword v140, v[154:155], off
	v_add_u32_e32 v154, s39, v147
	v_ashrrev_i32_e32 v155, 31, v154
	v_lshl_add_u64 v[154:155], v[154:155], 2, s[2:3]
	global_load_dword v142, v[154:155], off
	v_readlane_b32 s46, v251, 58
	v_readlane_b32 s47, v251, 59
	v_or_b32_e32 v153, s39, v141
	s_movk_i32 s39, 0x2c00
	s_and_b64 vcc, exec, s[36:37]
	s_mov_b32 s68, s40
	s_mov_b64 s[48:49], s[44:45]
	s_waitcnt vmcnt(0)
	v_fmamk_f32 v140, v140, 0x3a000000, v233
	v_rsq_f32_e32 v140, v140
	v_fmamk_f32 v142, v142, 0x3a000000, v233
	v_rsq_f32_e32 v154, v142
	v_and_or_b32 v142, v234, 64, v141
	v_lshlrev_b32_e32 v155, 2, v142
	ds_bpermute_b32 v156, v155, v140
	ds_bpermute_b32 v152, v155, v140 offset:64
	ds_bpermute_b32 v146, v155, v154
	ds_bpermute_b32 v144, v155, v154 offset:64
	ds_bpermute_b32 v150, v155, v140 offset:128
	s_waitcnt lgkmcnt(0)
	v_pk_mul_f32 v[126:127], v[126:127], v[156:157] op_sel_hi:[1,0]
	ds_bpermute_b32 v142, v155, v154 offset:128
	v_mul_f32_e32 v157, 0xbfb8aa3b, v126
	v_exp_f32_e32 v157, v157
	ds_bpermute_b32 v148, v155, v140 offset:192
	ds_bpermute_b32 v140, v155, v154 offset:192
	v_lshl_or_b32 v154, s65, 7, v149
	v_add_f32_e32 v157, 1.0, v157
	v_rcp_f32_e32 v158, v157
	v_pk_mul_f32 v[118:119], v[118:119], v[156:157] op_sel_hi:[1,0]
	v_mul_f32_e32 v157, 0xbfb8aa3b, v127
	v_exp_f32_e32 v157, v157
	v_ashrrev_i32_e32 v155, 31, v154
	v_pk_mul_f32 v[110:111], v[110:111], v[152:153] op_sel_hi:[1,0]
	v_pk_mul_f32 v[106:107], v[106:107], v[152:153] op_sel_hi:[1,0]
	v_add_f32_e32 v157, 1.0, v157
	v_rcp_f32_e32 v159, v157
	v_pk_mul_f32 v[120:121], v[120:121], v[156:157] op_sel_hi:[1,0]
	v_pk_mul_f32 v[122:123], v[122:123], v[156:157] op_sel_hi:[1,0]
	v_pk_mul_f32 v[114:115], v[114:115], v[156:157] op_sel_hi:[1,0]
	v_pk_mul_f32 v[126:127], v[126:127], v[158:159]
	v_pk_mul_f32 v[116:117], v[116:117], v[156:157] op_sel_hi:[1,0]
	v_pk_mul_f32 v[118:119], v[118:119], v[126:127]
	v_pk_mul_f32 v[126:127], v[128:129], v[156:157] op_sel_hi:[1,0]
	v_pk_mul_f32 v[108:109], v[108:109], v[152:153] op_sel_hi:[1,0]
	v_mul_f32_e32 v128, 0xbfb8aa3b, v126
	v_mul_f32_e32 v129, 0xbfb8aa3b, v127
	v_exp_f32_e32 v128, v128
	v_exp_f32_e32 v129, v129
	v_pk_mul_f32 v[102:103], v[102:103], v[152:153] op_sel_hi:[1,0]
	v_pk_mul_f32 v[98:99], v[98:99], v[152:153] op_sel_hi:[1,0]
	v_add_f32_e32 v128, 1.0, v128
	v_add_f32_e32 v129, 1.0, v129
	v_rcp_f32_e32 v128, v128
	v_rcp_f32_e32 v129, v129
	v_pk_mul_f32 v[100:101], v[100:101], v[152:153] op_sel_hi:[1,0]
	v_pk_mul_f32 v[94:95], v[94:95], v[150:151] op_sel_hi:[1,0]
	v_pk_mul_f32 v[90:91], v[90:91], v[150:151] op_sel_hi:[1,0]
	v_pk_mul_f32 v[126:127], v[126:127], v[128:129]
	v_pk_mul_f32 v[92:93], v[92:93], v[150:151] op_sel_hi:[1,0]
	v_pk_mul_f32 v[120:121], v[120:121], v[126:127]
	v_mul_f32_e32 v126, 0xbfb8aa3b, v122
	v_mul_f32_e32 v127, 0xbfb8aa3b, v123
	v_exp_f32_e32 v126, v126
	v_exp_f32_e32 v127, v127
	v_pk_mul_f32 v[86:87], v[86:87], v[150:151] op_sel_hi:[1,0]
	v_pk_mul_f32 v[82:83], v[82:83], v[150:151] op_sel_hi:[1,0]
	v_add_f32_e32 v126, 1.0, v126
	v_add_f32_e32 v127, 1.0, v127
	v_rcp_f32_e32 v126, v126
	v_rcp_f32_e32 v127, v127
	v_pk_mul_f32 v[84:85], v[84:85], v[150:151] op_sel_hi:[1,0]
	s_waitcnt lgkmcnt(1)
; __device__ __forceinline__ unsigned pk2(float lo, float hi) { f32x2 v = {lo, hi}; bf16x2_t b = __builtin_convertvector(v, bf16x2_t); return __builtin_bit_cast(unsigned, b); }
;     __device__ __forceinline__ void operator()(const AccT& acc, const Unit& u, int wr, int wc, int fr, int fq) const {
;     ...
; #pragma unroll
;         for (int ai = 0; ai < 2; ++ai)
; #pragma unroll
;             for (int m = 0; m < 4; ++m) {
;                 const int row = row0 + ai * HALF + m * 16;
;                 const float rs = rsv[ai * 4 + m];
;                 float v[8];
; #pragma unroll
;                 for (int n = 0; n < 2; ++n)
; #pragma unroll
;                     for (int j = 0; j < 4; ++j) {
;                         const float g = acc[ai][0][m][n][j] * rs, up = acc[ai][1][m][n][j] * rs;
;                         const float sg = __builtin_amdgcn_rcpf(1.0f + __builtin_amdgcn_exp2f(-g * LOG2E));
;                         v[4 * n + j] = g * sg * up;
;                     }
;                 u32x4 w; w.x = pk2(v[0], v[1]); w.y = pk2(v[2], v[3]); w.z = pk2(v[4], v[5]); w.w = pk2(v[6], v[7]);
;                 *(u32x4*)(mid + (size_t)row * FF + col0) = w;
	v_pk_mul_f32 v[78:79], v[78:79], v[148:149] op_sel_hi:[1,0]
	v_pk_mul_f32 v[74:75], v[74:75], v[148:149] op_sel_hi:[1,0]
	v_pk_mul_f32 v[122:123], v[122:123], v[126:127]
	v_pk_mul_f32 v[76:77], v[76:77], v[148:149] op_sel_hi:[1,0]
	v_pk_mul_f32 v[122:123], v[114:115], v[122:123]
	v_pk_mul_f32 v[114:115], v[124:125], v[156:157] op_sel_hi:[1,0]
	v_pk_mul_f32 v[70:71], v[70:71], v[148:149] op_sel_hi:[1,0]
	v_mul_f32_e32 v124, 0xbfb8aa3b, v114
	v_mul_f32_e32 v125, 0xbfb8aa3b, v115
	v_exp_f32_e32 v124, v124
	v_exp_f32_e32 v125, v125
	v_pk_mul_f32 v[66:67], v[66:67], v[148:149] op_sel_hi:[1,0]
	v_pk_mul_f32 v[68:69], v[68:69], v[148:149] op_sel_hi:[1,0]
	v_add_f32_e32 v124, 1.0, v124
	v_add_f32_e32 v125, 1.0, v125
	v_rcp_f32_e32 v124, v124
	v_rcp_f32_e32 v125, v125
	v_pk_mul_f32 v[62:63], v[62:63], v[146:147] op_sel_hi:[1,0]
	v_pk_mul_f32 v[58:59], v[58:59], v[146:147] op_sel_hi:[1,0]
	v_pk_mul_f32 v[60:61], v[60:61], v[146:147] op_sel_hi:[1,0]
	v_pk_mul_f32 v[114:115], v[114:115], v[124:125]
	v_pk_mul_f32 v[54:55], v[54:55], v[146:147] op_sel_hi:[1,0]
	v_pk_mul_f32 v[124:125], v[116:117], v[114:115]
	v_cvt_pk_bf16_f32 v114, v118, v119
	v_mov_b64_e32 v[118:119], s[46:47]
	v_cvt_pk_bf16_f32 v115, v120, v121
	v_cvt_pk_bf16_f32 v116, v122, v123
	v_mad_i64_i32 v[122:123], s[46:47], v153, s39, v[118:119]
	v_lshlrev_b64 v[120:121], 1, v[154:155]
	v_cvt_pk_bf16_f32 v117, v124, v125
	v_lshl_add_u64 v[122:123], v[122:123], 0, v[120:121]
	global_store_dwordx4 v[122:123], v[114:117], off
	v_pk_mul_f32 v[50:51], v[50:51], v[146:147] op_sel_hi:[1,0]
	v_pk_mul_f32 v[52:53], v[52:53], v[146:147] op_sel_hi:[1,0]
	v_mul_f32_e32 v114, 0xbfb8aa3b, v110
	v_mul_f32_e32 v115, 0xbfb8aa3b, v111
	v_exp_f32_e32 v114, v114
	v_exp_f32_e32 v115, v115
	v_pk_mul_f32 v[46:47], v[46:47], v[144:145] op_sel_hi:[1,0]
	v_pk_mul_f32 v[42:43], v[42:43], v[144:145] op_sel_hi:[1,0]
	v_add_f32_e32 v114, 1.0, v114
	v_add_f32_e32 v115, 1.0, v115
	v_rcp_f32_e32 v114, v114
	v_rcp_f32_e32 v115, v115
	v_pk_mul_f32 v[44:45], v[44:45], v[144:145] op_sel_hi:[1,0]
	v_pk_mul_f32 v[38:39], v[38:39], v[144:145] op_sel_hi:[1,0]
	v_pk_mul_f32 v[34:35], v[34:35], v[144:145] op_sel_hi:[1,0]
	v_pk_mul_f32 v[110:111], v[110:111], v[114:115]
	v_pk_mul_f32 v[36:37], v[36:37], v[144:145] op_sel_hi:[1,0]
	v_pk_mul_f32 v[106:107], v[106:107], v[110:111]
	v_pk_mul_f32 v[110:111], v[112:113], v[152:153] op_sel_hi:[1,0]
	v_pk_mul_f32 v[30:31], v[30:31], v[142:143] op_sel_hi:[1,0]
	v_mul_f32_e32 v112, 0xbfb8aa3b, v110
	v_mul_f32_e32 v113, 0xbfb8aa3b, v111
	v_exp_f32_e32 v112, v112
	v_exp_f32_e32 v113, v113
	v_pk_mul_f32 v[26:27], v[26:27], v[142:143] op_sel_hi:[1,0]
	v_pk_mul_f32 v[28:29], v[28:29], v[142:143] op_sel_hi:[1,0]
	v_add_f32_e32 v112, 1.0, v112
	v_add_f32_e32 v113, 1.0, v113
	v_rcp_f32_e32 v112, v112
	v_rcp_f32_e32 v113, v113
	v_pk_mul_f32 v[22:23], v[22:23], v[142:143] op_sel_hi:[1,0]
	v_pk_mul_f32 v[18:19], v[18:19], v[142:143] op_sel_hi:[1,0]
	v_pk_mul_f32 v[20:21], v[20:21], v[142:143] op_sel_hi:[1,0]
	v_pk_mul_f32 v[110:111], v[110:111], v[112:113]
	s_waitcnt lgkmcnt(0)
	v_pk_mul_f32 v[14:15], v[14:15], v[140:141] op_sel_hi:[1,0]
	v_pk_mul_f32 v[108:109], v[108:109], v[110:111]
	v_mul_f32_e32 v110, 0xbfb8aa3b, v102
	v_mul_f32_e32 v111, 0xbfb8aa3b, v103
	v_exp_f32_e32 v110, v110
	v_exp_f32_e32 v111, v111
	v_pk_mul_f32 v[10:11], v[10:11], v[140:141] op_sel_hi:[1,0]
	v_pk_mul_f32 v[12:13], v[12:13], v[140:141] op_sel_hi:[1,0]
	v_add_f32_e32 v110, 1.0, v110
	v_add_f32_e32 v111, 1.0, v111
	v_rcp_f32_e32 v110, v110
	v_rcp_f32_e32 v111, v111
	v_pk_mul_f32 v[6:7], v[6:7], v[140:141] op_sel_hi:[1,0]
	v_pk_mul_f32 v[2:3], v[2:3], v[140:141] op_sel_hi:[1,0]
	v_pk_mul_f32 v[4:5], v[4:5], v[140:141] op_sel_hi:[1,0]
	v_pk_mul_f32 v[102:103], v[102:103], v[110:111]
	v_or_b32_e32 v110, 16, v153
	v_pk_mul_f32 v[102:103], v[98:99], v[102:103]
	v_pk_mul_f32 v[98:99], v[104:105], v[152:153] op_sel_hi:[1,0]
	s_mov_b32 s65, s38
	v_mul_f32_e32 v104, 0xbfb8aa3b, v98
	v_mul_f32_e32 v105, 0xbfb8aa3b, v99
	v_exp_f32_e32 v104, v104
	v_exp_f32_e32 v105, v105
	v_add_f32_e32 v104, 1.0, v104
	v_add_f32_e32 v105, 1.0, v105
	v_rcp_f32_e32 v104, v104
	v_rcp_f32_e32 v105, v105
	s_nop 0
	v_pk_mul_f32 v[98:99], v[98:99], v[104:105]
	s_nop 0
	v_pk_mul_f32 v[104:105], v[100:101], v[98:99]
	v_cvt_pk_bf16_f32 v100, v102, v103
	v_mad_i64_i32 v[102:103], s[46:47], v110, s39, v[118:119]
	v_cvt_pk_bf16_f32 v98, v106, v107
	v_cvt_pk_bf16_f32 v99, v108, v109
	v_cvt_pk_bf16_f32 v101, v104, v105
	v_lshl_add_u64 v[102:103], v[102:103], 0, v[120:121]
	global_store_dwordx4 v[102:103], v[98:101], off
	s_nop 1
	v_mul_f32_e32 v98, 0xbfb8aa3b, v94
	v_mul_f32_e32 v99, 0xbfb8aa3b, v95
	v_exp_f32_e32 v98, v98
	v_exp_f32_e32 v99, v99
	v_add_f32_e32 v98, 1.0, v98
	v_add_f32_e32 v99, 1.0, v99
	v_rcp_f32_e32 v98, v98
	v_rcp_f32_e32 v99, v99
	s_nop 0
	v_pk_mul_f32 v[94:95], v[94:95], v[98:99]
	s_nop 0
	v_pk_mul_f32 v[90:91], v[90:91], v[94:95]
	v_pk_mul_f32 v[94:95], v[96:97], v[150:151] op_sel_hi:[1,0]
	s_nop 0
	v_mul_f32_e32 v96, 0xbfb8aa3b, v94
	v_mul_f32_e32 v97, 0xbfb8aa3b, v95
	v_exp_f32_e32 v96, v96
	v_exp_f32_e32 v97, v97
	v_add_f32_e32 v96, 1.0, v96
	v_add_f32_e32 v97, 1.0, v97
	v_rcp_f32_e32 v96, v96
	v_rcp_f32_e32 v97, v97
	s_nop 0
	v_pk_mul_f32 v[94:95], v[94:95], v[96:97]
	s_nop 0
	v_pk_mul_f32 v[92:93], v[92:93], v[94:95]
	v_mul_f32_e32 v94, 0xbfb8aa3b, v86
	v_mul_f32_e32 v95, 0xbfb8aa3b, v87
	v_exp_f32_e32 v94, v94
	v_exp_f32_e32 v95, v95
	v_add_f32_e32 v94, 1.0, v94
	v_add_f32_e32 v95, 1.0, v95
	v_rcp_f32_e32 v94, v94
	v_rcp_f32_e32 v95, v95
	s_nop 0
	v_pk_mul_f32 v[86:87], v[86:87], v[94:95]
	s_nop 0
	v_pk_mul_f32 v[86:87], v[82:83], v[86:87]
; __device__ __forceinline__ unsigned pk2(float lo, float hi) { f32x2 v = {lo, hi}; bf16x2_t b = __builtin_convertvector(v, bf16x2_t); return __builtin_bit_cast(unsigned, b); }
;     __device__ __forceinline__ void operator()(const AccT& acc, const Unit& u, int wr, int wc, int fr, int fq) const {
;     ...
;             for (int m = 0; m < 4; ++m) {
;                 const int row = row0 + ai * HALF + m * 16;
;                 const float rs = rsv[ai * 4 + m];
;                 float v[8];
; #pragma unroll
;                 for (int n = 0; n < 2; ++n)
; #pragma unroll
;                     for (int j = 0; j < 4; ++j) {
;                         const float g = acc[ai][0][m][n][j] * rs, up = acc[ai][1][m][n][j] * rs;
;                         const float sg = __builtin_amdgcn_rcpf(1.0f + __builtin_amdgcn_exp2f(-g * LOG2E));
;                         v[4 * n + j] = g * sg * up;
;                     }
;                 u32x4 w; w.x = pk2(v[0], v[1]); w.y = pk2(v[2], v[3]); w.z = pk2(v[4], v[5]); w.w = pk2(v[6], v[7]);
;                 *(u32x4*)(mid + (size_t)row * FF + col0) = w;
	v_pk_mul_f32 v[82:83], v[88:89], v[150:151] op_sel_hi:[1,0]
	v_or_b32_e32 v94, 32, v153
	v_mul_f32_e32 v88, 0xbfb8aa3b, v82
	v_mul_f32_e32 v89, 0xbfb8aa3b, v83
	v_exp_f32_e32 v88, v88
	v_exp_f32_e32 v89, v89
	v_add_f32_e32 v88, 1.0, v88
	v_add_f32_e32 v89, 1.0, v89
	v_rcp_f32_e32 v88, v88
	v_rcp_f32_e32 v89, v89
	s_nop 0
	v_pk_mul_f32 v[82:83], v[82:83], v[88:89]
	s_nop 0
	v_pk_mul_f32 v[88:89], v[84:85], v[82:83]
	v_cvt_pk_bf16_f32 v84, v86, v87
	v_mad_i64_i32 v[86:87], s[46:47], v94, s39, v[118:119]
	v_cvt_pk_bf16_f32 v82, v90, v91
	v_cvt_pk_bf16_f32 v83, v92, v93
	v_cvt_pk_bf16_f32 v85, v88, v89
	v_lshl_add_u64 v[86:87], v[86:87], 0, v[120:121]
	global_store_dwordx4 v[86:87], v[82:85], off
	s_nop 1
	v_mul_f32_e32 v82, 0xbfb8aa3b, v78
	v_mul_f32_e32 v83, 0xbfb8aa3b, v79
	v_exp_f32_e32 v82, v82
	v_exp_f32_e32 v83, v83
	v_add_f32_e32 v82, 1.0, v82
	v_add_f32_e32 v83, 1.0, v83
	v_rcp_f32_e32 v82, v82
	v_rcp_f32_e32 v83, v83
	s_nop 0
	v_pk_mul_f32 v[78:79], v[78:79], v[82:83]
	s_nop 0
	v_pk_mul_f32 v[74:75], v[74:75], v[78:79]
	v_pk_mul_f32 v[78:79], v[80:81], v[148:149] op_sel_hi:[1,0]
	s_nop 0
	v_mul_f32_e32 v80, 0xbfb8aa3b, v78
	v_mul_f32_e32 v81, 0xbfb8aa3b, v79
	v_exp_f32_e32 v80, v80
	v_exp_f32_e32 v81, v81
	v_add_f32_e32 v80, 1.0, v80
	v_add_f32_e32 v81, 1.0, v81
	v_rcp_f32_e32 v80, v80
	v_rcp_f32_e32 v81, v81
	s_nop 0
	v_pk_mul_f32 v[78:79], v[78:79], v[80:81]
	s_nop 0
	v_pk_mul_f32 v[76:77], v[76:77], v[78:79]
	v_mul_f32_e32 v78, 0xbfb8aa3b, v70
	v_mul_f32_e32 v79, 0xbfb8aa3b, v71
	v_exp_f32_e32 v78, v78
	v_exp_f32_e32 v79, v79
	v_add_f32_e32 v78, 1.0, v78
	v_add_f32_e32 v79, 1.0, v79
	v_rcp_f32_e32 v78, v78
	v_rcp_f32_e32 v79, v79
	s_nop 0
	v_pk_mul_f32 v[70:71], v[70:71], v[78:79]
	s_nop 0
	v_pk_mul_f32 v[70:71], v[66:67], v[70:71]
	v_pk_mul_f32 v[66:67], v[72:73], v[148:149] op_sel_hi:[1,0]
	v_or_b32_e32 v78, 48, v153
	v_mul_f32_e32 v72, 0xbfb8aa3b, v66
	v_mul_f32_e32 v73, 0xbfb8aa3b, v67
	v_exp_f32_e32 v72, v72
	v_exp_f32_e32 v73, v73
	v_add_f32_e32 v72, 1.0, v72
	v_add_f32_e32 v73, 1.0, v73
	v_rcp_f32_e32 v72, v72
	v_rcp_f32_e32 v73, v73
	s_nop 0
	v_pk_mul_f32 v[66:67], v[66:67], v[72:73]
	s_nop 0
	v_pk_mul_f32 v[72:73], v[68:69], v[66:67]
	v_cvt_pk_bf16_f32 v68, v70, v71
	v_mad_i64_i32 v[70:71], s[46:47], v78, s39, v[118:119]
	v_cvt_pk_bf16_f32 v66, v74, v75
	v_cvt_pk_bf16_f32 v67, v76, v77
	v_cvt_pk_bf16_f32 v69, v72, v73
	v_lshl_add_u64 v[70:71], v[70:71], 0, v[120:121]
	global_store_dwordx4 v[70:71], v[66:69], off
	s_nop 1
	v_mul_f32_e32 v66, 0xbfb8aa3b, v62
	v_mul_f32_e32 v67, 0xbfb8aa3b, v63
	v_exp_f32_e32 v66, v66
	v_exp_f32_e32 v67, v67
	v_add_u32_e32 v68, 0x80, v153
	v_add_f32_e32 v66, 1.0, v66
	v_add_f32_e32 v67, 1.0, v67
	v_rcp_f32_e32 v66, v66
	v_rcp_f32_e32 v67, v67
	s_nop 0
	v_pk_mul_f32 v[62:63], v[62:63], v[66:67]
	s_nop 0
	v_pk_mul_f32 v[58:59], v[58:59], v[62:63]
	v_pk_mul_f32 v[62:63], v[64:65], v[146:147] op_sel_hi:[1,0]
	s_nop 0
	v_mul_f32_e32 v64, 0xbfb8aa3b, v62
	v_mul_f32_e32 v65, 0xbfb8aa3b, v63
	v_exp_f32_e32 v64, v64
	v_exp_f32_e32 v65, v65
	v_add_f32_e32 v64, 1.0, v64
	v_add_f32_e32 v65, 1.0, v65
	v_rcp_f32_e32 v64, v64
	v_rcp_f32_e32 v65, v65
	s_nop 0
	v_pk_mul_f32 v[62:63], v[62:63], v[64:65]
	s_nop 0
	v_pk_mul_f32 v[60:61], v[60:61], v[62:63]
	v_mul_f32_e32 v62, 0xbfb8aa3b, v54
	v_mul_f32_e32 v63, 0xbfb8aa3b, v55
	v_exp_f32_e32 v62, v62
	v_exp_f32_e32 v63, v63
	v_add_f32_e32 v62, 1.0, v62
	v_add_f32_e32 v63, 1.0, v63
	v_rcp_f32_e32 v62, v62
	v_rcp_f32_e32 v63, v63
	s_nop 0
	v_pk_mul_f32 v[54:55], v[54:55], v[62:63]
	s_nop 0
	v_pk_mul_f32 v[54:55], v[50:51], v[54:55]
	v_pk_mul_f32 v[50:51], v[56:57], v[146:147] op_sel_hi:[1,0]
	s_nop 0
	v_mul_f32_e32 v56, 0xbfb8aa3b, v50
	v_mul_f32_e32 v57, 0xbfb8aa3b, v51
	v_exp_f32_e32 v56, v56
	v_exp_f32_e32 v57, v57
	v_add_f32_e32 v56, 1.0, v56
	v_add_f32_e32 v57, 1.0, v57
	v_rcp_f32_e32 v56, v56
	v_rcp_f32_e32 v57, v57
	s_nop 0
	v_pk_mul_f32 v[50:51], v[50:51], v[56:57]
	s_nop 0
	v_pk_mul_f32 v[56:57], v[52:53], v[50:51]
	v_cvt_pk_bf16_f32 v52, v54, v55
	v_mad_i64_i32 v[54:55], s[46:47], v68, s39, v[118:119]
	v_cvt_pk_bf16_f32 v50, v58, v59
	v_cvt_pk_bf16_f32 v51, v60, v61
	v_cvt_pk_bf16_f32 v53, v56, v57
	v_lshl_add_u64 v[54:55], v[54:55], 0, v[120:121]
	global_store_dwordx4 v[54:55], v[50:53], off
	s_nop 1
	v_mul_f32_e32 v50, 0xbfb8aa3b, v46
	v_mul_f32_e32 v51, 0xbfb8aa3b, v47
	v_exp_f32_e32 v50, v50
	v_exp_f32_e32 v51, v51
	v_add_f32_e32 v50, 1.0, v50
	v_add_f32_e32 v51, 1.0, v51
	v_rcp_f32_e32 v50, v50
	v_rcp_f32_e32 v51, v51
	s_nop 0
	v_pk_mul_f32 v[46:47], v[46:47], v[50:51]
	s_nop 0
	v_pk_mul_f32 v[42:43], v[42:43], v[46:47]
	v_pk_mul_f32 v[46:47], v[48:49], v[144:145] op_sel_hi:[1,0]
	s_nop 0
	v_mul_f32_e32 v48, 0xbfb8aa3b, v46
	v_mul_f32_e32 v49, 0xbfb8aa3b, v47
	v_exp_f32_e32 v48, v48
	v_exp_f32_e32 v49, v49
	v_add_f32_e32 v48, 1.0, v48
; __device__ __forceinline__ unsigned pk2(float lo, float hi) { f32x2 v = {lo, hi}; bf16x2_t b = __builtin_convertvector(v, bf16x2_t); return __builtin_bit_cast(unsigned, b); }
;     __device__ __forceinline__ void operator()(const AccT& acc, const Unit& u, int wr, int wc, int fr, int fq) const {
;     ...
;             for (int m = 0; m < 4; ++m) {
;                 const int row = row0 + ai * HALF + m * 16;
;                 const float rs = rsv[ai * 4 + m];
;                 float v[8];
; #pragma unroll
;                 for (int n = 0; n < 2; ++n)
; #pragma unroll
;                     for (int j = 0; j < 4; ++j) {
;                         const float g = acc[ai][0][m][n][j] * rs, up = acc[ai][1][m][n][j] * rs;
;                         const float sg = __builtin_amdgcn_rcpf(1.0f + __builtin_amdgcn_exp2f(-g * LOG2E));
;                         v[4 * n + j] = g * sg * up;
;                     }
;                 u32x4 w; w.x = pk2(v[0], v[1]); w.y = pk2(v[2], v[3]); w.z = pk2(v[4], v[5]); w.w = pk2(v[6], v[7]);
;                 *(u32x4*)(mid + (size_t)row * FF + col0) = w;
	v_add_f32_e32 v49, 1.0, v49
	v_rcp_f32_e32 v48, v48
	v_rcp_f32_e32 v49, v49
	s_nop 0
	v_pk_mul_f32 v[46:47], v[46:47], v[48:49]
	s_nop 0
	v_pk_mul_f32 v[44:45], v[44:45], v[46:47]
	v_mul_f32_e32 v46, 0xbfb8aa3b, v38
	v_mul_f32_e32 v47, 0xbfb8aa3b, v39
	v_exp_f32_e32 v46, v46
	v_exp_f32_e32 v47, v47
	v_add_f32_e32 v46, 1.0, v46
	v_add_f32_e32 v47, 1.0, v47
	v_rcp_f32_e32 v46, v46
	v_rcp_f32_e32 v47, v47
	s_nop 0
	v_pk_mul_f32 v[38:39], v[38:39], v[46:47]
	s_nop 0
	v_pk_mul_f32 v[38:39], v[34:35], v[38:39]
	v_pk_mul_f32 v[34:35], v[40:41], v[144:145] op_sel_hi:[1,0]
	v_add_u32_e32 v46, 0x90, v153
	v_mul_f32_e32 v40, 0xbfb8aa3b, v34
	v_mul_f32_e32 v41, 0xbfb8aa3b, v35
	v_exp_f32_e32 v40, v40
	v_exp_f32_e32 v41, v41
	v_add_f32_e32 v40, 1.0, v40
	v_add_f32_e32 v41, 1.0, v41
	v_rcp_f32_e32 v40, v40
	v_rcp_f32_e32 v41, v41
	s_nop 0
	v_pk_mul_f32 v[34:35], v[34:35], v[40:41]
	s_nop 0
	v_pk_mul_f32 v[40:41], v[36:37], v[34:35]
	v_cvt_pk_bf16_f32 v36, v38, v39
	v_mad_i64_i32 v[38:39], s[46:47], v46, s39, v[118:119]
	v_cvt_pk_bf16_f32 v34, v42, v43
	v_cvt_pk_bf16_f32 v35, v44, v45
	v_cvt_pk_bf16_f32 v37, v40, v41
	v_lshl_add_u64 v[38:39], v[38:39], 0, v[120:121]
	global_store_dwordx4 v[38:39], v[34:37], off
	s_nop 1
	v_mul_f32_e32 v34, 0xbfb8aa3b, v30
	v_mul_f32_e32 v35, 0xbfb8aa3b, v31
	v_exp_f32_e32 v34, v34
	v_exp_f32_e32 v35, v35
	v_add_f32_e32 v34, 1.0, v34
	v_add_f32_e32 v35, 1.0, v35
	v_rcp_f32_e32 v34, v34
	v_rcp_f32_e32 v35, v35
	s_nop 0
	v_pk_mul_f32 v[30:31], v[30:31], v[34:35]
	s_nop 0
	v_pk_mul_f32 v[26:27], v[26:27], v[30:31]
	v_pk_mul_f32 v[30:31], v[32:33], v[142:143] op_sel_hi:[1,0]
	s_nop 0
	v_mul_f32_e32 v32, 0xbfb8aa3b, v30
	v_mul_f32_e32 v33, 0xbfb8aa3b, v31
	v_exp_f32_e32 v32, v32
	v_exp_f32_e32 v33, v33
	v_add_f32_e32 v32, 1.0, v32
	v_add_f32_e32 v33, 1.0, v33
	v_rcp_f32_e32 v32, v32
	v_rcp_f32_e32 v33, v33
	s_nop 0
	v_pk_mul_f32 v[30:31], v[30:31], v[32:33]
	s_nop 0
	v_pk_mul_f32 v[28:29], v[28:29], v[30:31]
	v_mul_f32_e32 v30, 0xbfb8aa3b, v22
	v_mul_f32_e32 v31, 0xbfb8aa3b, v23
	v_exp_f32_e32 v30, v30
	v_exp_f32_e32 v31, v31
	v_add_f32_e32 v30, 1.0, v30
	v_add_f32_e32 v31, 1.0, v31
	v_rcp_f32_e32 v30, v30
	v_rcp_f32_e32 v31, v31
	s_nop 0
	v_pk_mul_f32 v[22:23], v[22:23], v[30:31]
	s_nop 0
	v_pk_mul_f32 v[22:23], v[18:19], v[22:23]
	v_pk_mul_f32 v[18:19], v[24:25], v[142:143] op_sel_hi:[1,0]
	v_add_u32_e32 v30, 0xa0, v153
	v_mul_f32_e32 v24, 0xbfb8aa3b, v18
	v_mul_f32_e32 v25, 0xbfb8aa3b, v19
	v_exp_f32_e32 v24, v24
	v_exp_f32_e32 v25, v25
	v_add_f32_e32 v24, 1.0, v24
	v_add_f32_e32 v25, 1.0, v25
	v_rcp_f32_e32 v24, v24
	v_rcp_f32_e32 v25, v25
	s_nop 0
	v_pk_mul_f32 v[18:19], v[18:19], v[24:25]
	s_nop 0
	v_pk_mul_f32 v[24:25], v[20:21], v[18:19]
	v_cvt_pk_bf16_f32 v20, v22, v23
	v_mad_i64_i32 v[22:23], s[46:47], v30, s39, v[118:119]
	v_cvt_pk_bf16_f32 v18, v26, v27
	v_cvt_pk_bf16_f32 v19, v28, v29
	v_cvt_pk_bf16_f32 v21, v24, v25
	v_lshl_add_u64 v[22:23], v[22:23], 0, v[120:121]
	global_store_dwordx4 v[22:23], v[18:21], off
	s_nop 1
	v_mul_f32_e32 v18, 0xbfb8aa3b, v14
	v_mul_f32_e32 v19, 0xbfb8aa3b, v15
	v_exp_f32_e32 v18, v18
	v_exp_f32_e32 v19, v19
	v_add_f32_e32 v18, 1.0, v18
	v_add_f32_e32 v19, 1.0, v19
	v_rcp_f32_e32 v18, v18
	v_rcp_f32_e32 v19, v19
	s_nop 0
	v_pk_mul_f32 v[14:15], v[14:15], v[18:19]
	s_nop 0
	v_pk_mul_f32 v[10:11], v[10:11], v[14:15]
	v_pk_mul_f32 v[14:15], v[16:17], v[140:141] op_sel_hi:[1,0]
	s_nop 0
	v_mul_f32_e32 v16, 0xbfb8aa3b, v14
	v_mul_f32_e32 v17, 0xbfb8aa3b, v15
	v_exp_f32_e32 v16, v16
	v_exp_f32_e32 v17, v17
	v_add_f32_e32 v16, 1.0, v16
	v_add_f32_e32 v17, 1.0, v17
	v_rcp_f32_e32 v16, v16
	v_rcp_f32_e32 v17, v17
	s_nop 0
	v_pk_mul_f32 v[14:15], v[14:15], v[16:17]
	s_nop 0
	v_pk_mul_f32 v[12:13], v[12:13], v[14:15]
	v_mul_f32_e32 v14, 0xbfb8aa3b, v6
	v_mul_f32_e32 v15, 0xbfb8aa3b, v7
	v_exp_f32_e32 v14, v14
	v_exp_f32_e32 v15, v15
	v_add_f32_e32 v14, 1.0, v14
	v_add_f32_e32 v15, 1.0, v15
	v_rcp_f32_e32 v14, v14
	v_rcp_f32_e32 v15, v15
	s_nop 0
	v_pk_mul_f32 v[6:7], v[6:7], v[14:15]
	s_nop 0
	v_pk_mul_f32 v[6:7], v[2:3], v[6:7]
	v_pk_mul_f32 v[2:3], v[8:9], v[140:141] op_sel_hi:[1,0]
	v_add_u32_e32 v14, 0xb0, v153
	v_mul_f32_e32 v8, 0xbfb8aa3b, v2
	v_mul_f32_e32 v9, 0xbfb8aa3b, v3
	v_exp_f32_e32 v8, v8
	v_exp_f32_e32 v9, v9
	v_add_f32_e32 v8, 1.0, v8
	v_add_f32_e32 v9, 1.0, v9
	v_rcp_f32_e32 v8, v8
	v_rcp_f32_e32 v9, v9
	s_nop 0
	v_pk_mul_f32 v[2:3], v[2:3], v[8:9]
	s_nop 0
	v_pk_mul_f32 v[8:9], v[4:5], v[2:3]
	v_cvt_pk_bf16_f32 v4, v6, v7
	v_mad_i64_i32 v[6:7], s[46:47], v14, s39, v[118:119]
	v_cvt_pk_bf16_f32 v2, v10, v11
	v_cvt_pk_bf16_f32 v3, v12, v13
	v_cvt_pk_bf16_f32 v5, v8, v9
	v_lshl_add_u64 v[6:7], v[6:7], 0, v[120:121]
	s_mov_b64 s[46:47], s[42:43]
	global_store_dwordx4 v[6:7], v[2:5], off
	s_cbranch_vccz .LBB0_87
	s_waitcnt vmcnt(0)
	s_cmpk_gt_u32 s52, 0xff
	s_cbranch_scc1 .LBB0_94
	s_barrier

; #define PG8_STAGE(bufoff, gbase, voff) do { _Pragma("unroll") for (int _i = 0; _i < 2; ++_i) \
;         __builtin_amdgcn_global_load_lds((const unsigned*)((const char*)(gbase) + (voff)[_i]), (LAS unsigned*)(lds + (bufoff) + ldsw + _i * 8192), 16, 0, 0); } while (0)
; #define PG8_LDA(dst, b, h) do { _Pragma("unroll") for (int m = 0; m < 4; ++m) _Pragma("unroll") for (int k = 0; k < 2; ++k) dst[m][k] = *(const LAS bf16x8*)(lds + PG8_SA(b, h) + aoff + m * 2048 + k * 1024); } while (0)
; #define PG8_LDB(dst, b, h) do { _Pragma("unroll") for (int n = 0; n < 2; ++n) _Pragma("unroll") for (int k = 0; k < 2; ++k) dst[n][k] = *(const LAS bf16x8*)(lds + PG8_SB(b, h) + boff + n * 2048 + k * 1024); } while (0)
; #define PG8_MMA(ai, bj, At, Bt) do { __builtin_amdgcn_s_setprio(1); _Pragma("unroll") for (int m = 0; m < 4; ++m) _Pragma("unroll") for (int n = 0; n < 2; ++n) _Pragma("unroll") for (int k = 0; k < 2; ++k) \
;         acc[ai][bj][m][n] = __builtin_amdgcn_mfma_f32_16x16x32_bf16(Bt[n][k], At[m][k], acc[ai][bj][m][n], 0, 0, 0); __builtin_amdgcn_s_setprio(0); } while (0)
; #define PG8_WAIT_V(n) asm volatile("s_waitcnt vmcnt(" #n ")" ::: "memory")
; #define PG8_WAIT_L(n) asm volatile("s_waitcnt lgkmcnt(" #n ")" ::: "memory")
; template <class Epi>
; __device__ __forceinline__ void gemm_phase(LAS unsigned char* lds, const Gemm g, const StaticOrder& S, const Epi& E) {
;     ...
;         for (int t = 0; t < nt; t += 2) {
;             const bool last = (t == nt - 2);
;             const char* a1 = cA + (size_t)(t + 1) * kstep;
;             const char* a2 = last ? nA : cA + (size_t)(t + 2) * kstep; const char* b2 = last ? nB : cB + (size_t)(t + 2) * kstep;
;             const char* a3 = a2 + kstep; const char* b3 = b2 + kstep;
;             PG8_LDB(B0, 0, 0); PG8_SCHED; PG8_LDA(At, 0, 0); PG8_STAGE(PG8_SA(1, 1), a1 + hstep, voffA);
;             PG8_WAIT_L(8); PG8_BAR; PG8_WAIT_L(0); PG8_MMA(0, 0, At, B0); PG8_BAR; PG8_SCHED;
;             PG8_LDB(B1, 0, 1); PG8_STAGE(PG8_SB(0, 0), b2, voffB);
;             PG8_BAR; PG8_WAIT_L(0); PG8_MMA(0, 1, At, B1); PG8_BAR;
;             PG8_LDA(At, 0, 1); PG8_STAGE(PG8_SA(0, 0), a2, voffA);
;             PG8_BAR; PG8_WAIT_L(0); PG8_MMA(1, 0, At, B0); PG8_BAR; PG8_SCHED;
;             PG8_STAGE(PG8_SB(0, 1), b2 + hstep, voffB);
;             PG8_WAIT_V(6); PG8_BAR; PG8_MMA(1, 1, At, B1); PG8_BAR;
.LBB0_654:
	s_add_i32 s84, s62, 2
	s_add_u32 s64, s60, 0x80
	s_addc_u32 s63, s61, 0
	s_add_i32 s85, 0, 0x10000
	s_cmp_eq_u32 s77, s62
	s_cselect_b32 s62, s2, s64
	s_cselect_b32 s63, s3, s63
	s_cselect_b32 s65, s41, s83
	s_cselect_b32 s64, s40, s82
	s_add_i32 m0, s70, 0xc000
	ds_read_b128 v[146:149], v243
	ds_read_b128 v[150:153], v243 offset:1024
	ds_read_b128 v[154:157], v243 offset:2048
	ds_read_b128 v[158:161], v243 offset:3072
	ds_read_b128 v[162:165], v243 offset:4096
	ds_read_b128 v[166:169], v243 offset:5120
	ds_read_b128 v[170:173], v243 offset:6144
	ds_read_b128 v[174:177], v243 offset:7168
	global_load_lds_dwordx4 v214, s[60:61]
	s_add_i32 m0, s70, 0xe000
	s_nop 0
	global_load_lds_dwordx4 v216, s[60:61]
	s_waitcnt lgkmcnt(8)
	s_barrier
	s_waitcnt lgkmcnt(0)
	v_mfma_f32_16x16x32_bf16 v[142:145], v[58:61], v[146:149], v[142:145]
	v_mfma_f32_16x16x32_bf16 v[138:141], v[66:69], v[146:149], v[138:141]
	v_mfma_f32_16x16x32_bf16 v[126:129], v[58:61], v[154:157], v[126:129]
	v_mfma_f32_16x16x32_bf16 v[122:125], v[66:69], v[154:157], v[122:125]
	v_mfma_f32_16x16x32_bf16 v[110:113], v[58:61], v[162:165], v[110:113]
	v_mfma_f32_16x16x32_bf16 v[106:109], v[66:69], v[162:165], v[106:109]
	v_mfma_f32_16x16x32_bf16 v[94:97], v[58:61], v[170:173], v[94:97]
	v_mfma_f32_16x16x32_bf16 v[90:93], v[66:69], v[170:173], v[90:93]
	v_mfma_f32_16x16x32_bf16 v[142:145], v[62:65], v[150:153], v[142:145]
	v_mfma_f32_16x16x32_bf16 v[138:141], v[70:73], v[150:153], v[138:141]
	v_mfma_f32_16x16x32_bf16 v[126:129], v[62:65], v[158:161], v[126:129]
	v_mfma_f32_16x16x32_bf16 v[122:125], v[70:73], v[158:161], v[122:125]
	v_mfma_f32_16x16x32_bf16 v[110:113], v[62:65], v[166:169], v[110:113]
	v_mfma_f32_16x16x32_bf16 v[106:109], v[70:73], v[166:169], v[106:109]
	v_mfma_f32_16x16x32_bf16 v[94:97], v[62:65], v[174:177], v[94:97]
	v_mfma_f32_16x16x32_bf16 v[90:93], v[70:73], v[174:177], v[90:93]
	s_barrier
	s_add_i32 s86, 0, 0x14000
	s_add_i32 s85, s85, s69
	s_add_u32 s98, s64, s22
	s_addc_u32 s99, s65, s23
	s_mov_b32 m0, s85
	ds_read_b128 v[178:181], v194 offset:16384
	ds_read_b128 v[182:185], v194 offset:17408
	ds_read_b128 v[186:189], v194 offset:18432
	ds_read_b128 v[190:193], v194 offset:19456
	global_load_lds_dwordx4 v0, s[64:65]
	s_add_i32 m0, s85, 0x2000
	s_nop 0
	global_load_lds_dwordx4 v208, s[64:65]
	s_barrier
	s_waitcnt lgkmcnt(0)
	v_mfma_f32_16x16x32_bf16 v[134:137], v[178:181], v[146:149], v[134:137]
	v_mfma_f32_16x16x32_bf16 v[130:133], v[186:189], v[146:149], v[130:133]
	v_mfma_f32_16x16x32_bf16 v[118:121], v[178:181], v[154:157], v[118:121]
	v_mfma_f32_16x16x32_bf16 v[114:117], v[186:189], v[154:157], v[114:117]
	v_mfma_f32_16x16x32_bf16 v[102:105], v[178:181], v[162:165], v[102:105]
	v_mfma_f32_16x16x32_bf16 v[98:101], v[186:189], v[162:165], v[98:101]
	v_mfma_f32_16x16x32_bf16 v[86:89], v[178:181], v[170:173], v[86:89]
	v_mfma_f32_16x16x32_bf16 v[82:85], v[186:189], v[170:173], v[82:85]
	v_mfma_f32_16x16x32_bf16 v[134:137], v[182:185], v[150:153], v[134:137]
	v_mfma_f32_16x16x32_bf16 v[130:133], v[190:193], v[150:153], v[130:133]
	v_mfma_f32_16x16x32_bf16 v[118:121], v[182:185], v[158:161], v[118:121]
	v_mfma_f32_16x16x32_bf16 v[114:117], v[190:193], v[158:161], v[114:117]
	v_mfma_f32_16x16x32_bf16 v[102:105], v[182:185], v[166:169], v[102:105]
	v_mfma_f32_16x16x32_bf16 v[98:101], v[190:193], v[166:169], v[98:101]
	v_mfma_f32_16x16x32_bf16 v[86:89], v[182:185], v[174:177], v[86:89]
	v_mfma_f32_16x16x32_bf16 v[82:85], v[190:193], v[174:177], v[82:85]
	s_mov_b32 m0, s70
	s_add_u32 s100, s62, s22
	s_addc_u32 s101, s63, s23
	s_barrier
	ds_read_b128 v[146:149], v243 offset:16384
	ds_read_b128 v[150:153], v243 offset:17408
	ds_read_b128 v[154:157], v243 offset:18432
	ds_read_b128 v[158:161], v243 offset:19456
	ds_read_b128 v[162:165], v243 offset:20480
	ds_read_b128 v[166:169], v243 offset:21504
	ds_read_b128 v[170:173], v243 offset:22528
	ds_read_b128 v[174:177], v243 offset:23552
	global_load_lds_dwordx4 v212, s[62:63]
	s_mov_b32 m0, s71
	s_nop 0
	global_load_lds_dwordx4 v210, s[62:63]
	s_waitcnt vmcnt(10)
	s_barrier
	s_waitcnt lgkmcnt(0)
	v_mfma_f32_16x16x32_bf16 v[78:81], v[58:61], v[146:149], v[78:81]
	v_mfma_f32_16x16x32_bf16 v[74:77], v[66:69], v[146:149], v[74:77]
	v_mfma_f32_16x16x32_bf16 v[46:49], v[58:61], v[154:157], v[46:49]
	v_mfma_f32_16x16x32_bf16 v[42:45], v[66:69], v[154:157], v[42:45]
	v_mfma_f32_16x16x32_bf16 v[30:33], v[58:61], v[162:165], v[30:33]
	v_mfma_f32_16x16x32_bf16 v[26:29], v[66:69], v[162:165], v[26:29]
	v_mfma_f32_16x16x32_bf16 v[14:17], v[58:61], v[170:173], v[14:17]
	v_mfma_f32_16x16x32_bf16 v[10:13], v[66:69], v[170:173], v[10:13]
	v_mfma_f32_16x16x32_bf16 v[78:81], v[62:65], v[150:153], v[78:81]
	v_mfma_f32_16x16x32_bf16 v[74:77], v[70:73], v[150:153], v[74:77]
	v_mfma_f32_16x16x32_bf16 v[46:49], v[62:65], v[158:161], v[46:49]
	v_mfma_f32_16x16x32_bf16 v[42:45], v[70:73], v[158:161], v[42:45]
	v_mfma_f32_16x16x32_bf16 v[30:33], v[62:65], v[166:169], v[30:33]
	v_mfma_f32_16x16x32_bf16 v[26:29], v[70:73], v[166:169], v[26:29]
	v_mfma_f32_16x16x32_bf16 v[14:17], v[62:65], v[174:177], v[14:17]
	v_mfma_f32_16x16x32_bf16 v[10:13], v[70:73], v[174:177], v[10:13]
	s_barrier
	ds_read_b128 v[58:61], v194 offset:32768
	ds_read_b128 v[62:65], v194 offset:33792
	ds_read_b128 v[66:69], v194 offset:34816
	ds_read_b128 v[70:73], v194 offset:35840
	s_add_u32 s64, s64, s50
	s_addc_u32 s65, s65, 0
	s_add_i32 s85, s86, s69
	s_mov_b32 m0, s85
	s_add_u32 vcc_lo, s64, s22
	s_addc_u32 vcc_hi, s65, s23
	global_load_lds_dwordx4 v0, s[64:65]
	s_add_i32 m0, s85, 0x2000
	s_nop 0
	global_load_lds_dwordx4 v208, s[64:65]
	s_waitcnt vmcnt(6)
	s_barrier
; #define PG8_STAGE(bufoff, gbase, voff) do { _Pragma("unroll") for (int _i = 0; _i < 2; ++_i) \
;         __builtin_amdgcn_global_load_lds((const unsigned*)((const char*)(gbase) + (voff)[_i]), (LAS unsigned*)(lds + (bufoff) + ldsw + _i * 8192), 16, 0, 0); } while (0)
; #define PG8_LDA(dst, b, h) do { _Pragma("unroll") for (int m = 0; m < 4; ++m) _Pragma("unroll") for (int k = 0; k < 2; ++k) dst[m][k] = *(const LAS bf16x8*)(lds + PG8_SA(b, h) + aoff + m * 2048 + k * 1024); } while (0)
; #define PG8_LDB(dst, b, h) do { _Pragma("unroll") for (int n = 0; n < 2; ++n) _Pragma("unroll") for (int k = 0; k < 2; ++k) dst[n][k] = *(const LAS bf16x8*)(lds + PG8_SB(b, h) + boff + n * 2048 + k * 1024); } while (0)
; #define PG8_MMA(ai, bj, At, Bt) do { __builtin_amdgcn_s_setprio(1); _Pragma("unroll") for (int m = 0; m < 4; ++m) _Pragma("unroll") for (int n = 0; n < 2; ++n) _Pragma("unroll") for (int k = 0; k < 2; ++k) \
;         acc[ai][bj][m][n] = __builtin_amdgcn_mfma_f32_16x16x32_bf16(Bt[n][k], At[m][k], acc[ai][bj][m][n], 0, 0, 0); __builtin_amdgcn_s_setprio(0); } while (0)
; #define PG8_WAIT_V(n) asm volatile("s_waitcnt vmcnt(" #n ")" ::: "memory")
; #define PG8_WAIT_L(n) asm volatile("s_waitcnt lgkmcnt(" #n ")" ::: "memory")
; #define PG8_BAR __builtin_amdgcn_s_barrier()
; #define PG8_SCHED __builtin_amdgcn_sched_barrier(0)
; template <class Epi>
; __device__ __forceinline__ void gemm_phase(LAS unsigned char* lds, const Gemm g, const StaticOrder& S, const Epi& E) {
;     ...
;             PG8_WAIT_V(6); PG8_BAR; PG8_MMA(1, 1, At, B1); PG8_BAR;
;             PG8_LDB(B0, 1, 0); PG8_SCHED; PG8_LDA(At, 1, 0); PG8_STAGE(PG8_SA(0, 1), a2 + hstep, voffA);
;             PG8_WAIT_L(8); PG8_BAR; PG8_WAIT_L(0); PG8_MMA(0, 0, At, B0); PG8_BAR; PG8_SCHED;
;             PG8_LDB(B1, 1, 1); PG8_STAGE(PG8_SB(1, 0), b3, voffB);
;             PG8_BAR; PG8_WAIT_L(0); PG8_MMA(0, 1, At, B1); PG8_BAR;
;             PG8_LDA(At, 1, 1); PG8_STAGE(PG8_SA(1, 0), a3, voffA);
;             PG8_BAR; PG8_WAIT_L(0); PG8_MMA(1, 0, At, B0); PG8_BAR; PG8_SCHED;
	v_mfma_f32_16x16x32_bf16 v[54:57], v[178:181], v[146:149], v[54:57]
	v_mfma_f32_16x16x32_bf16 v[50:53], v[186:189], v[146:149], v[50:53]
	v_mfma_f32_16x16x32_bf16 v[38:41], v[178:181], v[154:157], v[38:41]
	v_mfma_f32_16x16x32_bf16 v[34:37], v[186:189], v[154:157], v[34:37]
	v_mfma_f32_16x16x32_bf16 v[22:25], v[178:181], v[162:165], v[22:25]
	v_mfma_f32_16x16x32_bf16 v[18:21], v[186:189], v[162:165], v[18:21]
	v_mfma_f32_16x16x32_bf16 v[6:9], v[178:181], v[170:173], v[6:9]
	v_mfma_f32_16x16x32_bf16 v[2:5], v[186:189], v[170:173], v[2:5]
	v_mfma_f32_16x16x32_bf16 v[54:57], v[182:185], v[150:153], v[54:57]
	v_mfma_f32_16x16x32_bf16 v[50:53], v[190:193], v[150:153], v[50:53]
	v_mfma_f32_16x16x32_bf16 v[38:41], v[182:185], v[158:161], v[38:41]
	v_mfma_f32_16x16x32_bf16 v[34:37], v[190:193], v[158:161], v[34:37]
	v_mfma_f32_16x16x32_bf16 v[22:25], v[182:185], v[166:169], v[22:25]
	v_mfma_f32_16x16x32_bf16 v[18:21], v[190:193], v[166:169], v[18:21]
	v_mfma_f32_16x16x32_bf16 v[6:9], v[182:185], v[174:177], v[6:9]
	v_mfma_f32_16x16x32_bf16 v[2:5], v[190:193], v[174:177], v[2:5]
	s_add_i32 s64, 0, 0x18000
	s_barrier
	s_add_u32 s62, s62, s50
	s_addc_u32 s63, s63, 0
	s_mov_b32 m0, s72
	ds_read_b128 v[146:149], v243 offset:32768
	ds_read_b128 v[150:153], v243 offset:33792
	ds_read_b128 v[154:157], v243 offset:34816
	ds_read_b128 v[158:161], v243 offset:35840
	ds_read_b128 v[162:165], v243 offset:36864
	ds_read_b128 v[166:169], v243 offset:37888
	ds_read_b128 v[170:173], v243 offset:38912
	ds_read_b128 v[174:177], v243 offset:39936
	global_load_lds_dwordx4 v212, s[62:63]
	s_mov_b32 m0, s73
	s_nop 0
	global_load_lds_dwordx4 v210, s[62:63]
	s_waitcnt lgkmcnt(8)
	s_barrier
	s_waitcnt lgkmcnt(0)
	v_mfma_f32_16x16x32_bf16 v[142:145], v[58:61], v[146:149], v[142:145]
	v_mfma_f32_16x16x32_bf16 v[138:141], v[66:69], v[146:149], v[138:141]
	v_mfma_f32_16x16x32_bf16 v[126:129], v[58:61], v[154:157], v[126:129]
	v_mfma_f32_16x16x32_bf16 v[122:125], v[66:69], v[154:157], v[122:125]
	v_mfma_f32_16x16x32_bf16 v[110:113], v[58:61], v[162:165], v[110:113]
	v_mfma_f32_16x16x32_bf16 v[106:109], v[66:69], v[162:165], v[106:109]
	v_mfma_f32_16x16x32_bf16 v[94:97], v[58:61], v[170:173], v[94:97]
	v_mfma_f32_16x16x32_bf16 v[90:93], v[66:69], v[170:173], v[90:93]
	v_mfma_f32_16x16x32_bf16 v[142:145], v[62:65], v[150:153], v[142:145]
	v_mfma_f32_16x16x32_bf16 v[138:141], v[70:73], v[150:153], v[138:141]
	v_mfma_f32_16x16x32_bf16 v[126:129], v[62:65], v[158:161], v[126:129]
	v_mfma_f32_16x16x32_bf16 v[122:125], v[70:73], v[158:161], v[122:125]
	v_mfma_f32_16x16x32_bf16 v[110:113], v[62:65], v[166:169], v[110:113]
	v_mfma_f32_16x16x32_bf16 v[106:109], v[70:73], v[166:169], v[106:109]
	v_mfma_f32_16x16x32_bf16 v[94:97], v[62:65], v[174:177], v[94:97]
	v_mfma_f32_16x16x32_bf16 v[90:93], v[70:73], v[174:177], v[90:93]
	s_barrier
	s_add_i32 s62, 0, 0x1c000
	s_add_i32 s63, s64, s69
	s_mov_b32 m0, s63
	ds_read_b128 v[178:181], v194 offset:49152
	ds_read_b128 v[182:185], v194 offset:50176
	ds_read_b128 v[186:189], v194 offset:51200
	ds_read_b128 v[190:193], v194 offset:52224
	global_load_lds_dwordx4 v0, s[98:99]
	s_add_i32 m0, s63, 0x2000
	s_nop 0
	global_load_lds_dwordx4 v208, s[98:99]
	s_barrier
	s_waitcnt lgkmcnt(0)
	v_mfma_f32_16x16x32_bf16 v[134:137], v[178:181], v[146:149], v[134:137]
	v_mfma_f32_16x16x32_bf16 v[130:133], v[186:189], v[146:149], v[130:133]
	v_mfma_f32_16x16x32_bf16 v[118:121], v[178:181], v[154:157], v[118:121]
	v_mfma_f32_16x16x32_bf16 v[114:117], v[186:189], v[154:157], v[114:117]
	v_mfma_f32_16x16x32_bf16 v[102:105], v[178:181], v[162:165], v[102:105]
	v_mfma_f32_16x16x32_bf16 v[98:101], v[186:189], v[162:165], v[98:101]
	v_mfma_f32_16x16x32_bf16 v[86:89], v[178:181], v[170:173], v[86:89]
	v_mfma_f32_16x16x32_bf16 v[82:85], v[186:189], v[170:173], v[82:85]
	v_mfma_f32_16x16x32_bf16 v[134:137], v[182:185], v[150:153], v[134:137]
	v_mfma_f32_16x16x32_bf16 v[130:133], v[190:193], v[150:153], v[130:133]
	v_mfma_f32_16x16x32_bf16 v[118:121], v[182:185], v[158:161], v[118:121]
	v_mfma_f32_16x16x32_bf16 v[114:117], v[190:193], v[158:161], v[114:117]
	v_mfma_f32_16x16x32_bf16 v[102:105], v[182:185], v[166:169], v[102:105]
	v_mfma_f32_16x16x32_bf16 v[98:101], v[190:193], v[166:169], v[98:101]
	v_mfma_f32_16x16x32_bf16 v[86:89], v[182:185], v[174:177], v[86:89]
	v_mfma_f32_16x16x32_bf16 v[82:85], v[190:193], v[174:177], v[82:85]
	s_mov_b32 m0, s75
	s_barrier
	ds_read_b128 v[146:149], v243 offset:49152
	ds_read_b128 v[150:153], v243 offset:50176
	ds_read_b128 v[154:157], v243 offset:51200
	ds_read_b128 v[158:161], v243 offset:52224
	ds_read_b128 v[162:165], v243 offset:53248
	ds_read_b128 v[166:169], v243 offset:54272
	ds_read_b128 v[170:173], v243 offset:55296
	ds_read_b128 v[174:177], v243 offset:56320
	global_load_lds_dwordx4 v212, s[100:101]
	s_mov_b32 m0, s76
	s_nop 0
	global_load_lds_dwordx4 v210, s[100:101]
	s_waitcnt vmcnt(10)
	s_barrier
	s_waitcnt lgkmcnt(0)
	v_mfma_f32_16x16x32_bf16 v[78:81], v[58:61], v[146:149], v[78:81]
	v_mfma_f32_16x16x32_bf16 v[74:77], v[66:69], v[146:149], v[74:77]
	v_mfma_f32_16x16x32_bf16 v[46:49], v[58:61], v[154:157], v[46:49]
	v_mfma_f32_16x16x32_bf16 v[42:45], v[66:69], v[154:157], v[42:45]
	v_mfma_f32_16x16x32_bf16 v[30:33], v[58:61], v[162:165], v[30:33]
	v_mfma_f32_16x16x32_bf16 v[26:29], v[66:69], v[162:165], v[26:29]
	v_mfma_f32_16x16x32_bf16 v[14:17], v[58:61], v[170:173], v[14:17]
	v_mfma_f32_16x16x32_bf16 v[10:13], v[66:69], v[170:173], v[10:13]
	v_mfma_f32_16x16x32_bf16 v[78:81], v[62:65], v[150:153], v[78:81]
	v_mfma_f32_16x16x32_bf16 v[74:77], v[70:73], v[150:153], v[74:77]
	v_mfma_f32_16x16x32_bf16 v[46:49], v[62:65], v[158:161], v[46:49]
	v_mfma_f32_16x16x32_bf16 v[42:45], v[70:73], v[158:161], v[42:45]
	v_mfma_f32_16x16x32_bf16 v[30:33], v[62:65], v[166:169], v[30:33]
	v_mfma_f32_16x16x32_bf16 v[26:29], v[70:73], v[166:169], v[26:29]
	v_mfma_f32_16x16x32_bf16 v[14:17], v[62:65], v[174:177], v[14:17]
	v_mfma_f32_16x16x32_bf16 v[10:13], v[70:73], v[174:177], v[10:13]
	s_barrier
; #define PG8_BAR __builtin_amdgcn_s_barrier()
;     __device__ __forceinline__ void operator()(const AccT& acc, const Unit& u, int wr, int wc, int fr, int fq) const {
;         const int row0 = u.pm * BM + wr * 64 + fr, col0 = u.pn * BM + wc * 32 + 8 * fq;
;         f32x4 gv[2][2];
; #pragma unroll
;         for (int bj = 0; bj < 2; ++bj)
; #pragma unroll
;             for (int n = 0; n < 2; ++n) gv[bj][n] = *(const f32x4*)(g + col0 + bj * HALF + 4 * n);
; #pragma unroll
;         for (int ai = 0; ai < 2; ++ai) {
;             f32x4 xv[4][2][2];
; #pragma unroll
;             for (int m = 0; m < 4; ++m)
; #pragma unroll
;                 for (int bj = 0; bj < 2; ++bj) {
;                     const size_t p = (size_t)(row0 + ai * HALF + m * 16) * DM + col0 + bj * HALF;
;                     xv[m][bj][0] = __builtin_nontemporal_load((const f32x4*)(xin + p)); xv[m][bj][1] = __builtin_nontemporal_load((const f32x4*)(xin + p + 4));
;                 }
; #pragma unroll
;             for (int m = 0; m < 4; ++m) {
;                 const int row = row0 + ai * HALF + m * 16;
;                 float ssa = 0.f;
; #pragma unroll
;                 for (int bj = 0; bj < 2; ++bj) {
;                     const size_t p = (size_t)row * DM + col0 + bj * HALF;
;                     const f32x4 x0 = xv[m][bj][0] + acc[ai][bj][m][0] * alpha, x1 = xv[m][bj][1] + acc[ai][bj][m][1] * alpha;
;                     __builtin_nontemporal_store(x0, (f32x4*)(xout + p)); __builtin_nontemporal_store(x1, (f32x4*)(xout + p + 4));
;                     ssa += (x0[0] * x0[0] + x0[1] * x0[1]) + (x0[2] * x0[2] + x0[3] * x0[3]) + (x1[0] * x1[0] + x1[1] * x1[1]) + (x1[2] * x1[2] + x1[3] * x1[3]);
;                     const f32x4 h0 = x0 * gv[bj][0], h1 = x1 * gv[bj][1];
;                     u32x4 w; w.x = pk2(h0[0], h0[1]); w.y = pk2(h0[2], h0[3]); w.z = pk2(h1[0], h1[1]); w.w = pk2(h1[2], h1[3]);
;                     *(u32x4*)(h + p) = w;
;                 }
;                 ssa += __shfl_xor(ssa, 16); ssa += __shfl_xor(ssa, 32);
; template <class Epi>
; __device__ __forceinline__ void gemm_phase(LAS unsigned char* lds, const Gemm g, const StaticOrder& S, const Epi& E) {
;     ...
;             PG8_BAR; PG8_WAIT_L(0); PG8_MMA(1, 0, At, B0); PG8_BAR; PG8_SCHED;
;             PG8_STAGE(PG8_SB(1, 1), b3 + hstep, voffB);
;             PG8_WAIT_V(6); PG8_BAR; PG8_MMA(1, 1, At, B1); PG8_BAR;
	ds_read_b128 v[58:61], v194
	ds_read_b128 v[62:65], v194 offset:1024
	ds_read_b128 v[66:69], v194 offset:2048
	ds_read_b128 v[70:73], v194 offset:3072
	s_add_i32 s62, s62, s69
	s_mov_b32 m0, s62
	s_nop 0
	global_load_lds_dwordx4 v0, vcc
	s_add_i32 m0, s62, 0x2000
	s_nop 0
	global_load_lds_dwordx4 v208, vcc
	s_waitcnt vmcnt(6)
	s_barrier
	v_mfma_f32_16x16x32_bf16 v[54:57], v[178:181], v[146:149], v[54:57]
	v_mfma_f32_16x16x32_bf16 v[50:53], v[186:189], v[146:149], v[50:53]
	v_mfma_f32_16x16x32_bf16 v[38:41], v[178:181], v[154:157], v[38:41]
	v_mfma_f32_16x16x32_bf16 v[34:37], v[186:189], v[154:157], v[34:37]
	v_mfma_f32_16x16x32_bf16 v[22:25], v[178:181], v[162:165], v[22:25]
	v_mfma_f32_16x16x32_bf16 v[18:21], v[186:189], v[162:165], v[18:21]
	v_mfma_f32_16x16x32_bf16 v[6:9], v[178:181], v[170:173], v[6:9]
	v_mfma_f32_16x16x32_bf16 v[2:5], v[186:189], v[170:173], v[2:5]
	v_mfma_f32_16x16x32_bf16 v[54:57], v[182:185], v[150:153], v[54:57]
	v_mfma_f32_16x16x32_bf16 v[50:53], v[190:193], v[150:153], v[50:53]
	v_mfma_f32_16x16x32_bf16 v[38:41], v[182:185], v[158:161], v[38:41]
	v_mfma_f32_16x16x32_bf16 v[34:37], v[190:193], v[158:161], v[34:37]
	v_mfma_f32_16x16x32_bf16 v[22:25], v[182:185], v[166:169], v[22:25]
	v_mfma_f32_16x16x32_bf16 v[18:21], v[190:193], v[166:169], v[18:21]
	v_mfma_f32_16x16x32_bf16 v[6:9], v[182:185], v[174:177], v[6:9]
	v_mfma_f32_16x16x32_bf16 v[2:5], v[190:193], v[174:177], v[2:5]
	s_add_u32 s60, s60, 0x100
	s_addc_u32 s61, s61, 0
	s_add_u32 s82, s82, 0x100
	s_addc_u32 s83, s83, 0
	s_cmp_ge_u32 s84, s74
	s_mov_b32 s62, s84
	s_barrier
	s_cbranch_scc0 .LBB0_654
	s_waitcnt lgkmcnt(0)
	v_lshl_or_b32 v218, s81, 8, v242
	v_ashrrev_i32_e32 v219, 31, v218
	v_lshl_add_u32 v220, s80, 8, v240
	v_lshlrev_b64 v[146:147], 2, v[218:219]
	v_ashrrev_i32_e32 v221, 31, v220
	v_lshl_add_u64 v[62:63], s[44:45], 0, v[146:147]
	v_lshl_add_u64 v[222:223], s[54:55], 0, v[146:147]
	v_lshlrev_b64 v[146:147], 13, v[220:221]
	v_lshl_add_u64 v[146:147], v[222:223], 0, v[146:147]
	global_load_dwordx4 v[66:69], v[62:63], off offset:16
	global_load_dwordx4 v[70:73], v[62:63], off
	global_load_dwordx4 v[58:61], v[62:63], off offset:528
	s_nop 0
	global_load_dwordx4 v[62:65], v[62:63], off offset:512
	s_nop 0
	global_load_dwordx4 v[246:249], v[146:147], off offset:16 nt
	global_load_dwordx4 v[202:205], v[146:147], off nt
	global_load_dwordx4 v[194:197], v[146:147], off offset:528 nt
	global_load_dwordx4 v[198:201], v[146:147], off offset:512 nt
	v_or_b32_e32 v228, 16, v220
	v_and_b32_e32 v149, 64, v234
	v_ashrrev_i32_e32 v229, 31, v228
	v_xor_b32_e32 v148, 16, v234
	v_add_u32_e32 v149, 64, v149
	v_lshlrev_b64 v[146:147], 13, v[228:229]
	v_or_b32_e32 v226, 32, v220
	v_cmp_lt_i32_e32 vcc, v148, v149
	v_lshl_add_u64 v[146:147], v[222:223], 0, v[146:147]
	v_ashrrev_i32_e32 v227, 31, v226
	v_cndmask_b32_e32 v148, v234, v148, vcc
	global_load_dwordx4 v[186:189], v[146:147], off offset:16 nt
	global_load_dwordx4 v[190:193], v[146:147], off nt
	global_load_dwordx4 v[178:181], v[146:147], off offset:528 nt
	global_load_dwordx4 v[182:185], v[146:147], off offset:512 nt
	v_lshlrev_b64 v[146:147], 13, v[226:227]
	v_or_b32_e32 v224, 48, v220
	v_lshlrev_b32_e32 v245, 2, v148
	v_xor_b32_e32 v148, 32, v234
	v_lshl_add_u64 v[146:147], v[222:223], 0, v[146:147]
	v_ashrrev_i32_e32 v225, 31, v224
	v_cmp_lt_i32_e32 vcc, v148, v149
	global_load_dwordx4 v[170:173], v[146:147], off offset:16 nt
	global_load_dwordx4 v[174:177], v[146:147], off nt
	global_load_dwordx4 v[154:157], v[146:147], off offset:528 nt
	global_load_dwordx4 v[158:161], v[146:147], off offset:512 nt
	v_lshlrev_b64 v[146:147], 13, v[224:225]
	v_cndmask_b32_e32 v148, v234, v148, vcc
	v_lshl_add_u64 v[150:151], v[222:223], 0, v[146:147]
	v_lshlrev_b32_e32 v244, 2, v148
	global_load_dwordx4 v[162:165], v[150:151], off offset:16 nt
	global_load_dwordx4 v[166:169], v[150:151], off nt
	global_load_dwordx4 v[146:149], v[150:151], off offset:528 nt
	s_nop 0
	global_load_dwordx4 v[150:153], v[150:151], off offset:512 nt
	v_lshlrev_b64 v[230:231], 11, v[220:221]
	v_readlane_b32 s60, v251, 56
	v_lshl_add_u64 v[230:231], v[230:231], 0, v[218:219]
	v_readlane_b32 s61, v251, 57
	v_readlane_b32 s62, v254, 8
	v_readlane_b32 s63, v254, 9
	s_waitcnt vmcnt(0)
	v_pk_fma_f32 v[140:141], s[58:59], v[140:141], v[248:249]
	v_pk_fma_f32 v[144:145], s[58:59], v[144:145], v[204:205]
	v_pk_fma_f32 v[142:143], s[46:47], v[142:143], v[202:203]
	v_lshl_add_u64 v[202:203], v[230:231], 2, s[60:61]
	v_pk_fma_f32 v[138:139], s[46:47], v[138:139], v[246:247]
	global_store_dwordx4 v[202:203], v[142:145], off nt
	global_store_dwordx4 v[202:203], v[138:141], off offset:16 nt
	v_mul_f32_e32 v202, v143, v143
	v_mul_f32_e32 v203, v145, v145
	v_fmac_f32_e32 v202, v142, v142
	v_fmac_f32_e32 v203, v144, v144
	v_add_f32_e32 v202, v202, v203
	v_mul_f32_e32 v203, v139, v139
	v_fmac_f32_e32 v203, v138, v138
	v_add_f32_e32 v202, v203, v202
	v_mul_f32_e32 v203, v141, v141
	v_fmac_f32_e32 v203, v140, v140
	v_add_f32_e32 v204, v203, v202
	v_pk_mul_f32 v[144:145], v[72:73], v[144:145]
	v_pk_mul_f32 v[142:143], v[70:71], v[142:143]
	v_pk_mul_f32 v[202:203], v[68:69], v[140:141]
	v_pk_mul_f32 v[140:141], v[66:67], v[138:139]
	v_cvt_pk_bf16_f32 v138, v142, v143
	v_cvt_pk_bf16_f32 v139, v144, v145
	v_cvt_pk_bf16_f32 v140, v140, v141
	v_cvt_pk_bf16_f32 v141, v202, v203
	v_lshl_add_u64 v[142:143], v[230:231], 1, s[62:63]
	v_or_b32_e32 v230, 0x80, v230
	global_store_dwordx4 v[142:143], v[138:141], off
	v_pk_fma_f32 v[136:137], s[58:59], v[136:137], v[200:201]
	v_pk_fma_f32 v[134:135], s[46:47], v[134:135], v[198:199]
	v_lshl_add_u64 v[138:139], v[230:231], 2, s[60:61]
	v_pk_fma_f32 v[132:133], s[58:59], v[132:133], v[196:197]
	v_pk_fma_f32 v[130:131], s[46:47], v[130:131], v[194:195]
	global_store_dwordx4 v[138:139], v[134:137], off nt
	global_store_dwordx4 v[138:139], v[130:133], off offset:16 nt
	v_mul_f32_e32 v138, v135, v135
	v_mul_f32_e32 v139, v137, v137
	v_fmac_f32_e32 v138, v134, v134
	v_fmac_f32_e32 v139, v136, v136
	v_add_f32_e32 v138, v138, v139
	v_mul_f32_e32 v139, v131, v131
	v_fmac_f32_e32 v139, v130, v130
	v_add_f32_e32 v138, v139, v138
	v_mul_f32_e32 v139, v133, v133
	v_fmac_f32_e32 v139, v132, v132
	v_add_f32_e32 v138, v139, v138
	v_add_f32_e32 v140, v204, v138
	v_pk_mul_f32 v[136:137], v[64:65], v[136:137]
	v_pk_mul_f32 v[134:135], v[62:63], v[134:135]
	v_pk_mul_f32 v[138:139], v[60:61], v[132:133]
	v_pk_mul_f32 v[132:133], v[58:59], v[130:131]
	v_cvt_pk_bf16_f32 v130, v134, v135
	v_cvt_pk_bf16_f32 v131, v136, v137
	v_cvt_pk_bf16_f32 v132, v132, v133
	v_cvt_pk_bf16_f32 v133, v138, v139
	v_lshl_add_u64 v[134:135], v[230:231], 1, s[62:63]
	global_store_dwordx4 v[134:135], v[130:133], off
	ds_bpermute_b32 v130, v245, v140
	v_lshl_add_u64 v[138:139], v[220:221], 2, s[56:57]
	s_waitcnt lgkmcnt(0)
	v_add_f32_e32 v130, v140, v130
	ds_bpermute_b32 v131, v244, v130
	s_and_saveexec_b64 s[60:61], s[36:37]
	s_cbranch_execz .LBB0_657
	s_waitcnt lgkmcnt(0)
	v_add_f32_e32 v130, v130, v131
	global_atomic_add_f32 v[138:139], v130, off
